# chain dma+stores plus gla_prep: raw-v LDS-DMA issued one task ahead into a second 32 KB LDS buffer (saddr form), task-top wait vmcnt(16), no mid-task drain
# speedup vs baseline: 1.0055x; 1.0055x over previous
; #define LAS __attribute__((address_space(3)))
; #define PP_FETCH(task_) do { const int c_ = (task_) >> 2, h_ = (task_) & 3; const size_t t0_ = (size_t)c_ * 64; \
;         n_lr = *(const f32x4*)(LR + t0_ * 32 + tid * 4); \
;         _Pragma("unroll") for (int r_ = 0; r_ < 8; ++r_) { const bf16_t* rp_ = PG + (t0_ + rg * 8 + r_) * 2048 + h_ * 128 + c0; n_q[r_] = *(const unsigned*)rp_; n_k[r_] = *(const unsigned*)(rp_ + 512); } } while (0)
; DI void phase_gla_prep(const Params& P, int l, int bid, int nb, LAS unsigned char* lds) {
;     const int tid = threadIdx.x, wid = tid >> 6, lane = tid & 63, dpl = lane & 7, rg = lane >> 3, r32 = lane & 31, hi = lane >> 5;
;     const bf16_t* PG = (const bf16_t*)(P.ws + WS_PG); const float* LR = (const float*)(P.ws + WS_LR);
;     const int c0 = wid * 16 + dpl * 2;
;     const int p0 = (c0 & ~15) | (c0 & 3) | ((c0 & 4) << 1) | ((c0 & 8) >> 1);
;     int hcur = -1;
;     f32x4 n_lr; unsigned n_q[8], n_k[8];
;     ...
;     if (bid < 2560) PP_FETCH(bid);
;     ...
;         { const int dir = wid >> 2, ti = (wid >> 1) & 1, tj = wid & 1; const int i = ti * 32 + r32, jr = tj * 32 + r32;
;           f32x16 acc; for (int x = 0; x < 16; ++x) acc[x] = 0.f;
; #pragma unroll
;           for (int s = 0; s < 8; ++s) { const int ch = 2 * s + hi;
;               const bf16x8 a = *(const LAS bf16x8*)(lds + PP_KD + dir * 16384 + jr * 256 + ((ch ^ (jr & 15)) << 4));
;               const bf16x8 b = *(const LAS bf16x8*)(lds + PP_QD + dir * 16384 + i * 256 + ((ch ^ (i & 15)) << 4));
;               acc = __builtin_amdgcn_mfma_f32_32x32x16_bf16(a, b, acc, 0, 0, 0); }
;           unsigned char* am = P.ws + GL_PD + ((size_t)dir * 2560 + task) * GL_PD_BYTES + 16384;
; #pragma unroll
;           for (int a4 = 0; a4 < 4; ++a4) { float v[4];
; #pragma unroll
;               for (int b4 = 0; b4 < 4; ++b4) { const int j = tj * 32 + 8 * a4 + 4 * hi + b4; const bool keep = dir ? (j >= i) : (j <= i); v[b4] = keep ? acc[a4 * 4 + b4] : 0.f; }
.LBB0_332:
	s_cmp_lt_i32 s72, 3
	s_cselect_b64 s[0:1], -1, 0
	s_cmp_gt_i32 s73, 2
	s_cselect_b64 s[2:3], -1, 0
	s_and_b64 s[0:1], s[0:1], s[2:3]
	s_andn2_b64 vcc, exec, s[0:1]
	s_cbranch_vccnz .LBB0_400
	s_cmpk_gt_i32 s33, 0x9ff
	v_and_b32_e32 v136, 0x3ff, v0
	s_cbranch_scc1 .LBB0_350
	v_lshrrev_b32_e32 v137, 6, v136
	v_and_b32_e32 v138, 7, v136
	v_lshlrev_b32_e32 v3, 2, v136
	v_lshlrev_b32_e32 v2, 4, v137
	v_and_or_b32 v4, v3, 8, v2
	v_lshlrev_b32_e32 v5, 1, v138
	v_and_b32_e32 v6, 4, v136
	v_bfe_u32 v9, v136, 3, 3
	v_and_or_b32 v6, v5, 2, v6
	v_lshrrev_b32_e32 v10, 3, v4
	v_bitop3_b32 v4, v9, v136, 7 bitop3:0x78
	s_add_u32 s74, s50, 0x10440000
	v_or_b32_e32 v8, v2, v5
	v_and_b32_e32 v5, 31, v136
	v_lshlrev_b32_e32 v11, 1, v6
	v_lshlrev_b32_e32 v32, 4, v4
	v_bfe_u32 v4, v136, 6, 1
	v_lshrrev_b32_e32 v6, 2, v136
	s_addc_u32 s75, s51, 0
	v_and_or_b32 v9, v6, 32, v5
	v_lshlrev_b32_e32 v6, 5, v4
	s_add_u32 s44, s50, 0x1f440000
	v_lshlrev_b32_e32 v2, 3, v5
	v_lshrrev_b32_e32 v12, 8, v136
	v_or_b32_e32 v5, v6, v5
	s_addc_u32 s45, s51, 0
	v_lshlrev_b32_e32 v13, 14, v12
	s_add_i32 s2, 0, 0x12000
	v_lshlrev_b32_e32 v5, 8, v5
	v_bfe_u32 v139, v136, 5, 1
	v_add3_u32 v140, s2, v13, v5
	v_lshlrev_b32_e32 v5, 8, v9
	v_add3_u32 v141, 0, v13, v5
	v_lshl_or_b32 v13, v139, 2, v6
	v_lshlrev_b32_e32 v6, 2, v8
	s_add_i32 s2, 0, 0x1a200
	v_add_u32_e32 v143, s2, v6
	s_add_i32 s2, 0, 0x1a400
	v_add_u32_e32 v144, s2, v6
	s_add_i32 s2, 0, 0x1a600
	v_add_u32_e32 v145, s2, v6
	s_add_i32 s2, 0, 0x1a800
	v_add_u32_e32 v146, s2, v6
	s_add_i32 s2, 0, 0x1aa00
	v_add_u32_e32 v147, s2, v6
	s_add_i32 s2, 0, 0x1ac00
	v_add_u32_e32 v148, s2, v6
	s_add_i32 s2, 0, 0x1ae00
	v_add_u32_e32 v149, s2, v6
	s_add_i32 s2, 0, 0x1b000
	v_add_u32_e32 v150, s2, v6
	s_add_i32 s2, 0, 0x1b200
	v_add_u32_e32 v151, s2, v6
	s_add_i32 s2, 0, 0x1b400
	v_add_u32_e32 v152, s2, v6
	s_add_i32 s2, 0, 0x1b600
	v_add_u32_e32 v153, s2, v6
	s_add_i32 s2, 0, 0x1b800
	v_add_u32_e32 v154, s2, v6
	s_add_i32 s2, 0, 0x1ba00
	v_add_u32_e32 v155, s2, v6
	s_add_i32 s2, 0, 0x1bc00
	v_and_b32_e32 v7, 63, v136
	v_and_b32_e32 v64, 56, v136
	v_add_u32_e32 v156, s2, v6
	s_add_i32 s2, 0, 0x1be00
	v_lshlrev_b32_e32 v24, 1, v8
	v_lshlrev_b32_e32 v30, 7, v8
	v_cmp_gt_u32_e64 s[0:1], 8, v7
	v_add_u32_e32 v157, s2, v6
	v_cmp_gt_u32_e64 s[2:3], 56, v7
	v_cmp_gt_u32_e64 s[4:5], 48, v7
	v_cmp_gt_u32_e64 s[6:7], 32, v7
	v_cmp_gt_u32_e64 s[8:9], 16, v7
	v_bitop3_b32 v7, v10, v136, 8 bitop3:0x78
	v_lshl_or_b32 v8, v64, 8, v11
	v_lshl_add_u32 v158, v7, 4, v8
	v_or_b32_e32 v7, 1, v64
	v_bitop3_b32 v8, v10, v7, 9 bitop3:0x78
	v_lshl_or_b32 v7, v7, 8, v11
	v_lshl_add_u32 v159, v8, 4, v7
	v_or_b32_e32 v7, 2, v64
	v_bitop3_b32 v8, v10, v7, 10 bitop3:0x78
	v_lshl_or_b32 v7, v7, 8, v11
	v_lshl_add_u32 v160, v8, 4, v7
	v_or_b32_e32 v7, 3, v64
	v_bitop3_b32 v8, v10, v7, 11 bitop3:0x78
	v_lshl_or_b32 v7, v7, 8, v11
	v_lshl_add_u32 v161, v8, 4, v7
	v_or_b32_e32 v7, 4, v64
	v_bitop3_b32 v8, v10, v7, 12 bitop3:0x78
	v_lshl_or_b32 v7, v7, 8, v11
	v_lshl_add_u32 v162, v8, 4, v7
	v_or_b32_e32 v7, 5, v64
	v_bitop3_b32 v8, v10, v7, 13 bitop3:0x78
	v_lshl_or_b32 v7, v7, 8, v11
	v_lshl_add_u32 v163, v8, 4, v7
	v_or_b32_e32 v7, 6, v64
	v_bitop3_b32 v8, v10, v7, 14 bitop3:0x78
	v_lshl_or_b32 v7, v7, 8, v11
	v_lshl_add_u32 v164, v8, 4, v7
	v_or_b32_e32 v7, 7, v64
	v_bitop3_b32 v8, v10, v7, 15 bitop3:0x78
	v_lshl_or_b32 v7, v7, 8, v11
	v_and_b32_e32 v14, 15, v136
	v_lshl_add_u32 v165, v8, 4, v7
	v_bitop3_b32 v7, v139, v136, 15 bitop3:0x78
	v_lshlrev_b32_e32 v166, 4, v7
	v_bitop3_b32 v7, v139, v14, 2 bitop3:0x36
	v_lshlrev_b32_e32 v167, 4, v7
	v_bitop3_b32 v7, v139, v14, 4 bitop3:0x36
	v_lshlrev_b32_e32 v168, 4, v7
	v_bitop3_b32 v7, v139, v14, 6 bitop3:0x36
	v_lshlrev_b32_e32 v169, 4, v7
	v_bitop3_b32 v7, v139, v14, 8 bitop3:0x36
	v_lshlrev_b32_e32 v170, 4, v7
	v_bitop3_b32 v7, v139, v14, 10 bitop3:0x36
	v_lshlrev_b32_e32 v171, 4, v7
	v_bitop3_b32 v7, v139, v14, 12 bitop3:0x36
	v_lshlrev_b32_e32 v172, 4, v7
	v_bitop3_b32 v7, v139, v14, 14 bitop3:0x36
	v_cmp_le_u32_e32 vcc, v13, v9
	s_movk_i32 s10, 0x100
	v_lshlrev_b32_e32 v173, 4, v7
	v_cndmask_b32_e64 v7, 0, 1, vcc
	v_cmp_ge_u32_e32 vcc, v13, v9
	v_cmp_lt_u32_e64 s[12:13], v13, v9
	v_lshlrev_b32_e32 v15, 2, v4
	v_cndmask_b32_e64 v8, 0, 1, vcc
	v_cmp_gt_u32_e32 vcc, s10, v136
	v_lshrrev_b32_e32 v65, 1, v136
	v_lshlrev_b32_e32 v17, 3, v139
	v_cndmask_b32_e32 v7, v8, v7, vcc
	v_and_b32_e32 v7, 1, v7
	v_cmp_eq_u32_e64 s[10:11], 1, v7
	v_or_b32_e32 v7, 1, v13
	v_cndmask_b32_e64 v8, 0, 1, s[12:13]
	v_cmp_ge_u32_e64 s[12:13], v7, v9
	v_bfe_u32 v16, v136, 1, 3
	v_add_u32_e32 v76, 0x200, v136
	v_cndmask_b32_e64 v7, 0, 1, s[12:13]
	v_cndmask_b32_e32 v7, v7, v8, vcc
	v_and_b32_e32 v7, 1, v7
	v_cmp_eq_u32_e64 s[12:13], 1, v7
	v_or_b32_e32 v7, 2, v13
	v_cmp_le_u32_e64 s[14:15], v7, v9
	s_add_i32 s70, 0, 0x1a000
	v_add_u32_e32 v81, 0x600, v136
	v_cndmask_b32_e64 v8, 0, 1, s[14:15]
	v_cmp_ge_u32_e64 s[14:15], v7, v9
	s_add_u32 s78, s50, 0x29e70000
	s_addc_u32 s79, s51, 0
	v_cndmask_b32_e64 v7, 0, 1, s[14:15]
	v_cndmask_b32_e32 v7, v7, v8, vcc
	v_and_b32_e32 v7, 1, v7
	v_cmp_eq_u32_e64 s[14:15], 1, v7
	v_or_b32_e32 v7, 3, v13
	v_cmp_le_u32_e64 s[16:17], v7, v9
	s_lshl_b32 s76, s33, 8
	s_and_b32 s76, s76, 0x300
	v_cndmask_b32_e64 v8, 0, 1, s[16:17]
	v_cmp_ge_u32_e64 s[16:17], v7, v9
	s_add_u32 s80, s74, s76
	v_mov_b32_e32 v25, 0
	v_cndmask_b32_e64 v7, 0, 1, s[16:17]
	v_cndmask_b32_e32 v7, v7, v8, vcc
	v_and_b32_e32 v7, 1, v7
	v_cmp_eq_u32_e64 s[16:17], 1, v7
	v_bitop3_b32 v7, v15, v65, 7 bitop3:0x78
	v_lshl_or_b32 v38, v7, 4, v17
	v_or_b32_e32 v7, 8, v13
	v_cmp_le_u32_e64 s[18:19], v7, v9
	s_addc_u32 s81, s75, 0
; DI void phase_gla_prep(const Params& P, int l, int bid, int nb, LAS unsigned char* lds) {
;     const int tid = threadIdx.x, wid = tid >> 6, lane = tid & 63, dpl = lane & 7, rg = lane >> 3, r32 = lane & 31, hi = lane >> 5;
;     const bf16_t* PG = (const bf16_t*)(P.ws + WS_PG); const float* LR = (const float*)(P.ws + WS_LR);
;     const int c0 = wid * 16 + dpl * 2;
;     const int p0 = (c0 & ~15) | (c0 & 3) | ((c0 & 4) << 1) | ((c0 & 8) >> 1);
;     int hcur = -1;
;     f32x4 n_lr; unsigned n_q[8], n_k[8];
;     ...
;     if (bid < 2560) PP_FETCH(bid);
;     ...
;             unsigned char* pd = P.ws + GL_PD + ((size_t)dir * 2560 + task) * GL_PD_BYTES;
;             { const int dA = c0, dB = c0 + 1;
;               *(u32x4*)(pd + 24576 + dA * 128 + ((rg ^ ((dA >> 1) & 7)) << 4)) = (u32x4){kt0[0], kt0[1], kt0[2], kt0[3]};
;               *(u32x4*)(pd + 24576 + dB * 128 + ((rg ^ ((dB >> 1) & 7)) << 4)) = (u32x4){kt1[0], kt1[1], kt1[2], kt1[3]}; }
;             if (rg == 0) { float* dec = (float*)(P.ws + GL_DEC) + ((size_t)dir * 2560 + task) * 128; *(f32x2*)(dec + c0) = (f32x2){d0, d1}; }
;         }
;         __syncthreads();
;         { const int dir = wid >> 2, ti = (wid >> 1) & 1, tj = wid & 1; const int i = ti * 32 + r32, jr = tj * 32 + r32;
;           f32x16 acc; for (int x = 0; x < 16; ++x) acc[x] = 0.f;
; #pragma unroll
;           for (int s = 0; s < 8; ++s) { const int ch = 2 * s + hi;
;               const bf16x8 a = *(const LAS bf16x8*)(lds + PP_KD + dir * 16384 + jr * 256 + ((ch ^ (jr & 15)) << 4));
;               const bf16x8 b = *(const LAS bf16x8*)(lds + PP_QD + dir * 16384 + i * 256 + ((ch ^ (i & 15)) << 4));
;               acc = __builtin_amdgcn_mfma_f32_32x32x16_bf16(a, b, acc, 0, 0, 0); }
;           unsigned char* am = P.ws + GL_PD + ((size_t)dir * 2560 + task) * GL_PD_BYTES + 16384;
; #pragma unroll
;           for (int a4 = 0; a4 < 4; ++a4) { float v[4];
; #pragma unroll
;               for (int b4 = 0; b4 < 4; ++b4) { const int j = tj * 32 + 8 * a4 + 4 * hi + b4; const bool keep = dir ? (j >= i) : (j <= i); v[b4] = keep ? acc[a4 * 4 + b4] : 0.f; }
;               u32x2 w; w.x = pkbf(v[0], v[1]); w.y = pkbf(v[2], v[3]);
;               *(u32x2*)(am + i * 128 + ((((4 * tj + a4) ^ ((i >> 1) & 7)) << 4) | (hi << 3))) = w; } }
; #pragma unroll
;         for (int q = 0; q < 4; ++q) { const int e = q * 512 + tid, dir = e >> 10, o = (e & 1023) * 16;
	v_mul_u32_u24_e32 v34, 0xa00, v12
	v_cndmask_b32_e64 v8, 0, 1, s[18:19]
	v_cmp_ge_u32_e64 s[18:19], v7, v9
	v_lshlrev_b32_e32 v83, 12, v12
	v_lshlrev_b32_e32 v56, 12, v64
	v_cndmask_b32_e64 v7, 0, 1, s[18:19]
	v_cndmask_b32_e32 v7, v7, v8, vcc
	v_and_b32_e32 v7, 1, v7
	v_cmp_eq_u32_e64 s[18:19], 1, v7
	v_or_b32_e32 v7, 9, v13
	v_cmp_le_u32_e64 s[20:21], v7, v9
	v_mov_b32_e32 v57, v25
	s_movk_i32 s76, 0x1000
	v_cndmask_b32_e64 v8, 0, 1, s[20:21]
	v_cmp_ge_u32_e64 s[20:21], v7, v9
	v_lshlrev_b32_e32 v22, 4, v136
	v_mov_b32_e32 v23, v25
	v_cndmask_b32_e64 v7, 0, 1, s[20:21]
	v_cndmask_b32_e32 v7, v7, v8, vcc
	v_and_b32_e32 v7, 1, v7
	v_cmp_eq_u32_e64 s[20:21], 1, v7
	v_or_b32_e32 v7, 10, v13
	v_cmp_le_u32_e64 s[22:23], v7, v9
	v_lshl_add_u64 v[26:27], s[44:45], 0, v[22:23]
	v_and_b32_e32 v4, 0xff, v136
	v_cndmask_b32_e64 v8, 0, 1, s[22:23]
	v_cmp_ge_u32_e64 s[22:23], v7, v9
	v_add_u32_e32 v142, s70, v6
	v_lshl_add_u32 v79, v4, 1, 0
	v_cndmask_b32_e64 v7, 0, 1, s[22:23]
	v_cndmask_b32_e32 v7, v7, v8, vcc
	v_and_b32_e32 v7, 1, v7
	v_cmp_eq_u32_e64 s[22:23], 1, v7
	v_or_b32_e32 v7, 11, v13
	v_cmp_le_u32_e64 s[24:25], v7, v9
	v_lshlrev_b32_e32 v4, 7, v4
	v_mov_b32_e32 v5, v25
	v_cndmask_b32_e64 v8, 0, 1, s[24:25]
	v_cmp_ge_u32_e64 s[24:25], v7, v9
	v_lshl_add_u32 v175, v64, 7, 0
	v_lshl_add_u64 v[4:5], s[50:51], 0, v[4:5]
	v_cndmask_b32_e64 v7, 0, 1, s[24:25]
	v_cndmask_b32_e32 v7, v7, v8, vcc
	v_and_b32_e32 v7, 1, v7
	v_cmp_eq_u32_e64 s[24:25], 1, v7
	v_bitop3_b32 v7, v15, v16, 1 bitop3:0x36
	v_lshl_or_b32 v40, v7, 4, v17
	v_or_b32_e32 v7, 16, v13
	v_cmp_le_u32_e64 s[26:27], v7, v9
	v_and_b32_e32 v78, 0x7f, v136
	s_movk_i32 s71, 0x200
	v_cndmask_b32_e64 v8, 0, 1, s[26:27]
	v_cmp_ge_u32_e64 s[26:27], v7, v9
	v_lshl_add_u64 v[66:67], s[78:79], 0, v[22:23]
	v_add_u32_e32 v180, s70, v3
	v_cndmask_b32_e64 v7, 0, 1, s[26:27]
	v_cndmask_b32_e32 v7, v7, v8, vcc
	v_and_b32_e32 v7, 1, v7
	v_cmp_eq_u32_e64 s[26:27], 1, v7
	v_or_b32_e32 v7, 17, v13
	v_cmp_le_u32_e64 s[28:29], v7, v9
	v_lshlrev_b32_e32 v10, 4, v81
	v_lshl_add_u64 v[28:29], s[74:75], 0, v[24:25]
	v_cndmask_b32_e64 v8, 0, 1, s[28:29]
	v_cmp_ge_u32_e64 s[28:29], v7, v9
	v_lshlrev_b32_e32 v36, 7, v9
	v_and_b32_e32 v10, 0x3ff0, v10
	v_cndmask_b32_e64 v7, 0, 1, s[28:29]
	v_cndmask_b32_e32 v7, v7, v8, vcc
	v_and_b32_e32 v7, 1, v7
	v_cmp_eq_u32_e64 s[28:29], 1, v7
	v_or_b32_e32 v7, 18, v13
	v_cmp_le_u32_e64 s[30:31], v7, v9
	v_mov_b32_e32 v11, v25
	s_mov_b32 s77, 0
	v_cndmask_b32_e64 v8, 0, 1, s[30:31]
	v_cmp_ge_u32_e64 s[30:31], v7, v9
	v_mov_b32_e32 v31, v25
	v_mov_b32_e32 v33, v25
	v_cndmask_b32_e64 v7, 0, 1, s[30:31]
	v_cndmask_b32_e32 v7, v7, v8, vcc
	v_and_b32_e32 v7, 1, v7
	v_cmp_eq_u32_e64 s[30:31], 1, v7
	v_or_b32_e32 v7, 19, v13
	v_cmp_le_u32_e64 s[34:35], v7, v9
	v_mov_b32_e32 v35, v25
	v_mov_b32_e32 v37, v25
	v_cndmask_b32_e64 v8, 0, 1, s[34:35]
	v_cmp_ge_u32_e64 s[34:35], v7, v9
	v_mov_b32_e32 v39, v25
	v_mov_b32_e32 v41, v25
	v_cndmask_b32_e64 v7, 0, 1, s[34:35]
	v_cndmask_b32_e32 v7, v7, v8, vcc
	v_and_b32_e32 v7, 1, v7
	v_cmp_eq_u32_e64 s[34:35], 1, v7
	v_bitop3_b32 v7, v15, v16, 2 bitop3:0x36
	v_lshl_or_b32 v42, v7, 4, v17
	v_or_b32_e32 v7, 24, v13
	v_cmp_le_u32_e64 s[36:37], v7, v9
	v_mov_b32_e32 v43, v25
	v_mov_b32_e32 v45, v25
	v_cndmask_b32_e64 v8, 0, 1, s[36:37]
	v_cmp_ge_u32_e64 s[36:37], v7, v9
	v_mov_b32_e32 v47, v25
	v_mov_b32_e32 v49, v25
	v_cndmask_b32_e64 v7, 0, 1, s[36:37]
	v_cndmask_b32_e32 v7, v7, v8, vcc
	v_and_b32_e32 v7, 1, v7
	v_cmp_eq_u32_e64 s[36:37], 1, v7
	v_or_b32_e32 v7, 25, v13
	v_cmp_le_u32_e64 s[38:39], v7, v9
	v_mov_b32_e32 v51, v25
	v_mov_b32_e32 v53, v25
	v_cndmask_b32_e64 v8, 0, 1, s[38:39]
	v_cmp_ge_u32_e64 s[38:39], v7, v9
	v_mov_b32_e32 v55, v25
	v_lshl_add_u64 v[72:73], s[78:79], 0, v[10:11]
	v_cndmask_b32_e64 v7, 0, 1, s[38:39]
	v_cndmask_b32_e32 v7, v7, v8, vcc
	v_and_b32_e32 v7, 1, v7
	v_cmp_eq_u32_e64 s[38:39], 1, v7
	v_or_b32_e32 v7, 26, v13
	v_cmp_le_u32_e64 s[40:41], v7, v9
	s_mov_b32 s96, 0xbfb8aa3b
	s_mov_b32 s97, 0xa000
	v_cndmask_b32_e64 v8, 0, 1, s[40:41]
	v_cmp_ge_u32_e64 s[40:41], v7, v9
	v_add_u32_e32 v205, v79, v83
	v_mov_b32_e32 v212, 0xa000
	v_cndmask_b32_e64 v7, 0, 1, s[40:41]
	v_cndmask_b32_e32 v7, v7, v8, vcc
	v_and_b32_e32 v7, 1, v7
	v_cmp_eq_u32_e64 s[40:41], 1, v7
	v_or_b32_e32 v7, 27, v13
	v_cmp_le_u32_e64 s[42:43], v7, v9
	s_mov_b32 s84, s33
	s_nop 0
	v_cndmask_b32_e64 v8, 0, 1, s[42:43]
	v_cmp_ge_u32_e64 s[42:43], v7, v9
	v_mov_b32_e32 v9, v25
	s_nop 0
	v_cndmask_b32_e64 v7, 0, 1, s[42:43]
	v_cndmask_b32_e32 v7, v7, v8, vcc
	v_and_b32_e32 v7, 1, v7
	v_cmp_eq_u32_e64 s[42:43], 1, v7
	v_bitop3_b32 v7, v15, v16, 3 bitop3:0x36
	v_lshl_or_b32 v44, v7, 4, v17
	v_lshrrev_b32_e32 v7, 10, v76
	v_lshl_add_u32 v80, v7, 14, 0
	v_mul_u32_u24_e32 v46, 0xa00, v7
	v_lshrrev_b32_e32 v7, 10, v81
	v_lshl_add_u32 v82, v7, 14, 0
	v_mul_u32_u24_e32 v48, 0xa00, v7
	v_bitop3_b32 v7, v65, v12, 7 bitop3:0x6c
	v_lshlrev_b32_e32 v50, 4, v7
	v_lshrrev_b32_e32 v7, 8, v76
	v_lshlrev_b32_e32 v84, 12, v7
	v_bitop3_b32 v7, v7, v65, 7 bitop3:0x78
	v_lshlrev_b32_e32 v52, 4, v7
	v_or_b32_e32 v7, 4, v12
	v_lshlrev_b32_e32 v85, 12, v7
	v_bitop3_b32 v7, v12, v16, 4 bitop3:0x36
	v_lshl_add_u64 v[12:13], s[80:81], 0, v[24:25]
	s_ashr_i32 s80, s33, 2
	s_ashr_i32 s81, s80, 31
	s_lshl_b64 s[82:83], s[80:81], 18
	v_lshl_add_u64 v[12:13], v[12:13], 0, s[82:83]
	v_lshl_add_u64 v[12:13], v[12:13], 0, v[56:57]
	s_lshl_b64 s[80:81], s[80:81], 13
	v_add_co_u32_e32 v14, vcc, s76, v12
	s_add_u32 s44, s44, s80
	s_nop 0
	v_addc_co_u32_e32 v15, vcc, 0, v13, vcc
	s_movk_i32 s76, 0x2000
	s_addc_u32 s45, s45, s81
	v_add_co_u32_e32 v16, vcc, s76, v12
	v_lshlrev_b32_e32 v54, 4, v7
; #define LAS __attribute__((address_space(3)))
; #define PP_FETCH(task_) do { const int c_ = (task_) >> 2, h_ = (task_) & 3; const size_t t0_ = (size_t)c_ * 64; \
;         n_lr = *(const f32x4*)(LR + t0_ * 32 + tid * 4); \
;         _Pragma("unroll") for (int r_ = 0; r_ < 8; ++r_) { const bf16_t* rp_ = PG + (t0_ + rg * 8 + r_) * 2048 + h_ * 128 + c0; n_q[r_] = *(const unsigned*)rp_; n_k[r_] = *(const unsigned*)(rp_ + 512); } } while (0)
; DI void phase_gla_prep(const Params& P, int l, int bid, int nb, LAS unsigned char* lds) {
;     ...
;     if (bid < 2560) PP_FETCH(bid);
;     f32x2 bbs[2] = {{0.f, 0.f}, {0.f, 0.f}};
;     for (int task = bid; task < 2560; task += nb) {
;         const int c = task >> 2, h = task & 3;
;         __syncthreads();
;         if (h != hcur) { hcur = h;
;             for (int e = tid; e < 2 * 16 * 128; e += NTHR) { const int dir = e >> 11, k = (e >> 7) & 15, cc = e & 127;
;                 ((LAS float*)(lds + PP_W))[e] = (dir ? P.w_gk_b : P.w_gk_f)[(size_t)l * 16 * 512 + k * 512 + h * 128 + cc]; }
;             bbs[0] = *(const f32x2*)(P.b_gk_f + l * 512 + h * 128 + c0); bbs[1] = *(const f32x2*)(P.b_gk_b + l * 512 + h * 128 + c0); }
;         *(LAS f32x4*)(lds + PP_LR + tid * 16) = n_lr;
;         unsigned qw[8], kw[8];
; #pragma unroll
;         for (int r = 0; r < 8; ++r) { qw[r] = n_q[r]; kw[r] = n_k[r]; }
;         asm volatile("" : "+v"(qw[0]), "+v"(qw[1]), "+v"(qw[2]), "+v"(qw[3]), "+v"(qw[4]), "+v"(qw[5]), "+v"(qw[6]), "+v"(qw[7]), "+v"(kw[0]), "+v"(kw[1]), "+v"(kw[2]), "+v"(kw[3]), "+v"(kw[4]), "+v"(kw[5]), "+v"(kw[6]), "+v"(kw[7]) :: "memory");
;         __builtin_amdgcn_sched_barrier(0);
;         { const int wu = __builtin_amdgcn_readfirstlane(wid);
; #pragma unroll
;           for (int q = 0; q < 4; ++q) { const int row = wu * 8 + q * 2 + (lane >> 5);
;               __builtin_amdgcn_global_load_lds((const unsigned*)(PG + ((size_t)c * 64 + row) * 2048 + 1024 + h * 256 + (lane & 31) * 8), (LAS unsigned*)(lds + PP_V + (wu * 8 + q * 2) * 512), 16, 0, 0); } }
;         if (task + nb < 2560) PP_FETCH(task + nb);
	s_nop 0
	v_addc_co_u32_e32 v17, vcc, 0, v13, vcc
	global_load_dwordx4 v[18:21], v22, s[44:45]
	global_load_dword v174, v[16:17], off offset:-4096
	global_load_dword v176, v[16:17], off
	global_load_dword v177, v[16:17], off offset:1024
	s_movk_i32 s44, 0x3000
	v_add_co_u32_e32 v16, vcc, s44, v12
	s_movk_i32 s44, 0x4000
	s_nop 0
	v_addc_co_u32_e32 v17, vcc, 0, v13, vcc
	v_add_co_u32_e32 v58, vcc, s44, v12
	s_movk_i32 s44, 0x5000
	s_nop 0
	v_addc_co_u32_e32 v59, vcc, 0, v13, vcc
	v_add_co_u32_e32 v60, vcc, s44, v12
	s_movk_i32 s44, 0x6000
	s_nop 0
	v_addc_co_u32_e32 v61, vcc, 0, v13, vcc
	v_add_co_u32_e32 v62, vcc, s44, v12
	s_movk_i32 s44, 0x7000
	s_nop 0
	v_addc_co_u32_e32 v63, vcc, 0, v13, vcc
	global_load_dword v185, v[58:59], off offset:-4096
	global_load_dword v186, v[58:59], off
	global_load_dword v187, v[58:59], off offset:1024
	global_load_dword v193, v[62:63], off offset:-4096
	global_load_dword v199, v[62:63], off
	global_load_dword v200, v[62:63], off offset:1024
	v_add_co_u32_e32 v58, vcc, s44, v12
	v_lshrrev_b32_e32 v7, 8, v81
	s_nop 0
	v_addc_co_u32_e32 v59, vcc, 0, v13, vcc
	global_load_dword v178, v[12:13], off
	global_load_dword v179, v[12:13], off offset:1024
	global_load_dword v192, v[14:15], off offset:1024
	global_load_dword v196, v[16:17], off offset:1024
	global_load_dword v209, v[60:61], off offset:1024
	global_load_dword v213, v[58:59], off
	global_load_dword v214, v[58:59], off offset:1024
	v_lshlrev_b32_e32 v12, 12, v7
	v_bitop3_b32 v7, v7, v65, 7 bitop3:0x78
	v_lshlrev_b32_e32 v58, 4, v7
	v_mov_b32_e32 v7, v25
	v_lshl_add_u64 v[60:61], s[54:55], 0, v[6:7]
	v_lshl_add_u64 v[62:63], s[58:59], 0, v[6:7]
	v_lshl_add_u64 v[6:7], s[50:51], 0, v[6:7]
	s_mov_b64 s[44:45], 0x3b670000
	v_lshl_add_u64 v[64:65], v[6:7], 0, s[44:45]
	v_lshl_add_u64 v[6:7], s[50:51], 0, v[22:23]
	s_mov_b64 s[44:45], 0x30270000
	v_lshl_add_u64 v[70:71], v[6:7], 0, s[44:45]
	s_mov_b64 s[44:45], 0x36670000
	v_lshl_add_u64 v[74:75], v[4:5], 0, s[44:45]
	v_lshlrev_b32_e32 v4, 2, v76
	s_movk_i32 s76, 0x1e00
	v_and_or_b32 v181, v4, s76, v78
	v_add_u32_e32 v182, s70, v4
	v_or_b32_e32 v4, 0x1000, v3
	v_and_or_b32 v183, v4, s76, v78
	v_add_u32_e32 v184, s70, v4
	v_mov_b32_e32 v4, s57
	v_mov_b32_e32 v5, s53
	v_cmp_gt_u32_e32 vcc, s71, v136
	v_lshlrev_b32_e32 v8, 4, v76
	s_movk_i32 s44, 0xe00
	v_cndmask_b32_e32 v77, v4, v5, vcc
	v_mov_b32_e32 v4, s56
	v_mov_b32_e32 v5, s52
	v_cndmask_b32_e32 v76, v4, v5, vcc
	v_lshlrev_b32_e32 v4, 2, v81
	v_and_or_b32 v188, v4, s76, v78
	v_add_u32_e32 v189, s70, v4
	v_add_u32_e32 v4, 0x2800, v3
	v_and_or_b32 v190, v4, s76, v78
	v_add_u32_e32 v191, s70, v4
	v_or_b32_e32 v4, 0xc00, v136
	v_and_or_b32 v23, v3, s44, v78
	v_lshlrev_b32_e32 v5, 2, v4
	v_add_u32_e32 v3, 0x3800, v3
	v_and_or_b32 v194, v5, s76, v78
	v_and_or_b32 v197, v3, s76, v78
	v_lshlrev_b32_e32 v78, 1, v2
	v_mbcnt_lo_u32_b32 v2, -1, 0
	v_and_b32_e32 v8, 0x3ff0, v8
	v_mov_b32_e32 v24, v25
	v_mbcnt_hi_u32_b32 v210, -1, v2
	v_mov_b32_e32 v2, 0x80
	v_mov_b32_e32 v59, v25
	v_lshl_add_u64 v[68:69], s[78:79], 0, v[8:9]
	v_add_u32_e32 v195, s70, v5
	v_cmp_gt_u32_e64 s[44:45], s44, v4
	v_add_u32_e32 v198, s70, v3
	s_mov_b32 s70, -1
	s_mov_b64 s[78:79], 0x800
	s_mov_b64 s[80:81], 0x29e76000
	s_mov_b64 s[82:83], 0x29e74000
	v_add_u32_e32 v201, v80, v8
	v_add_u32_e32 v202, v82, v10
	v_add_u32_e32 v206, v79, v84
	v_add_u32_e32 v207, v79, v85
	v_add_u32_e32 v208, v79, v12
	v_lshl_or_b32 v211, v210, 2, v2
	v_mov_b64_e32 v[82:83], v[24:25]
	v_mov_b64_e32 v[80:81], v[24:25]
	s_ashr_i32 s68, s84, 2
	s_ashr_i32 s69, s68, 31
	s_lshl_b64 s[68:69], s[68:69], 18
	s_add_u32 s68, s74, s68
	s_addc_u32 s69, s75, s69
	s_add_u32 s68, s68, s78
	s_addc_u32 s69, s69, s79
	s_and_b32 s32, s84, 3
	s_lshl_b32 s32, s32, 9
	s_add_u32 s68, s68, s32
	s_addc_u32 s69, s69, 0
	v_readfirstlane_b32 s95, v137
	s_lshl_b32 s32, s95, 12
	s_addk_i32 s32, 0x2000
	s_lshl_b32 s95, s95, 3
	v_or_b32_e32 v85, s95, v139
	v_lshl_add_u32 v85, v85, 12, v78
	s_mov_b32 m0, s32
	s_nop 0
	global_load_lds_dwordx4 v85, s[68:69]
	v_add_u32_e32 v84, 0x2000, v85
	s_add_i32 m0, s32, 0x400
	s_nop 0
	global_load_lds_dwordx4 v84, s[68:69]
	v_add_u32_e32 v84, 0x4000, v85
	s_add_i32 m0, s32, 0x800
	s_nop 0
	global_load_lds_dwordx4 v84, s[68:69]
	v_add_u32_e32 v84, 0x6000, v85
	s_add_i32 m0, s32, 0xc00
	s_nop 0
	global_load_lds_dwordx4 v84, s[68:69]
	s_mov_b32 s66, 0x1c000
	s_mov_b32 s67, 0x1c000
	s_waitcnt vmcnt(0)
	s_branch .LBB0_336
; #define LAS __attribute__((address_space(3)))
; DI unsigned pkbf(float a, float b) { f32x2 v = {a, b}; bfx2 r = __builtin_convertvector(v, bfx2); return __builtin_bit_cast(unsigned, r); }
; DI void phase_gla_prep(const Params& P, int l, int bid, int nb, LAS unsigned char* lds) {
;     ...
;         { const int dir = wid >> 2, ti = (wid >> 1) & 1, tj = wid & 1; const int i = ti * 32 + r32, jr = tj * 32 + r32;
;           f32x16 acc; for (int x = 0; x < 16; ++x) acc[x] = 0.f;
; #pragma unroll
;           for (int s = 0; s < 8; ++s) { const int ch = 2 * s + hi;
;               const bf16x8 a = *(const LAS bf16x8*)(lds + PP_KD + dir * 16384 + jr * 256 + ((ch ^ (jr & 15)) << 4));
;               const bf16x8 b = *(const LAS bf16x8*)(lds + PP_QD + dir * 16384 + i * 256 + ((ch ^ (i & 15)) << 4));
;               acc = __builtin_amdgcn_mfma_f32_32x32x16_bf16(a, b, acc, 0, 0, 0); }
;           unsigned char* am = P.ws + GL_PD + ((size_t)dir * 2560 + task) * GL_PD_BYTES + 16384;
; #pragma unroll
;           for (int a4 = 0; a4 < 4; ++a4) { float v[4];
; #pragma unroll
;               for (int b4 = 0; b4 < 4; ++b4) { const int j = tj * 32 + 8 * a4 + 4 * hi + b4; const bool keep = dir ? (j >= i) : (j <= i); v[b4] = keep ? acc[a4 * 4 + b4] : 0.f; }
;               u32x2 w; w.x = pkbf(v[0], v[1]); w.y = pkbf(v[2], v[3]);
;               *(u32x2*)(am + i * 128 + ((((4 * tj + a4) ^ ((i >> 1) & 7)) << 4) | (hi << 3))) = w; } }
; #pragma unroll
;         for (int q = 0; q < 4; ++q) { const int e = q * 512 + tid, dir = e >> 10, o = (e & 1023) * 16;
;             *(u32x4*)(P.ws + GL_PD + ((size_t)dir * 2560 + task) * GL_PD_BYTES + o) = *(const LAS u32x4*)(lds + PP_QD + dir * 16384 + o); }
; #pragma unroll
;         for (int q = 0; q < 4; ++q) { const int e = q * 512 + tid, v = e & 255, jo = e >> 8; unsigned short t[8];
; #pragma unroll
;             for (int x = 0; x < 8; ++x) t[x] = *(const LAS unsigned short*)(lds + PP_V + (jo * 8 + x) * 512 + v * 2);
;             u32x4 w; w.x = t[0] | ((unsigned)t[1] << 16); w.y = t[2] | ((unsigned)t[3] << 16); w.z = t[4] | ((unsigned)t[5] << 16); w.w = t[6] | ((unsigned)t[7] << 16);
;             *(u32x4*)(P.ws + GL_VT + (size_t)task * 32768 + v * 128 + ((jo ^ ((v >> 1) & 7)) << 4)) = w; }
.LBB0_335:
	v_add_u32_e32 v2, v140, v166
	s_waitcnt lgkmcnt(0)
	s_barrier
	ds_read_b128 v[2:5], v2
	v_add_u32_e32 v6, v141, v166
	ds_read_b128 v[6:9], v6 offset:40960
	v_add_u32_e32 v79, v140, v167
	ds_read_b128 v[84:87], v79
	v_add_u32_e32 v79, v141, v167
	s_waitcnt lgkmcnt(1)
	v_mfma_f32_32x32x16_bf16 v[2:17], v[2:5], v[6:9], 0
	ds_read_b128 v[88:91], v79 offset:40960
	v_add_u32_e32 v79, v140, v168
	v_add_u32_e32 v96, v141, v172
	v_add_u32_e32 v97, v141, v173
	v_lshl_add_u64 v[100:101], s[84:85], 0, v[34:35]
	v_mov_b64_e32 v[102:103], s[50:51]
	s_and_b64 vcc, exec, s[86:87]
	s_waitcnt lgkmcnt(0)
	v_mfma_f32_32x32x16_bf16 v[2:17], v[84:87], v[88:91], v[2:17]
	ds_read_b128 v[84:87], v79
	v_add_u32_e32 v79, v141, v168
	ds_read_b128 v[88:91], v79 offset:40960
	v_add_u32_e32 v79, v140, v169
	s_waitcnt lgkmcnt(0)
	v_mfma_f32_32x32x16_bf16 v[2:17], v[84:87], v[88:91], v[2:17]
	ds_read_b128 v[84:87], v79
	v_add_u32_e32 v79, v141, v169
	ds_read_b128 v[88:91], v79 offset:40960
	v_add_u32_e32 v79, v140, v170
	s_waitcnt lgkmcnt(0)
	v_mfma_f32_32x32x16_bf16 v[2:17], v[84:87], v[88:91], v[2:17]
	ds_read_b128 v[84:87], v79
	v_add_u32_e32 v79, v141, v170
	ds_read_b128 v[88:91], v79 offset:40960
	v_add_u32_e32 v79, v140, v171
	s_waitcnt lgkmcnt(0)
	v_mfma_f32_32x32x16_bf16 v[2:17], v[84:87], v[88:91], v[2:17]
	ds_read_b128 v[84:87], v79
	v_add_u32_e32 v79, v141, v171
	ds_read_b128 v[88:91], v79 offset:40960
	v_add_u32_e32 v79, v140, v172
	ds_read_b128 v[92:95], v79
	s_waitcnt lgkmcnt(1)
	v_mfma_f32_32x32x16_bf16 v[2:17], v[84:87], v[88:91], v[2:17]
	ds_read_b128 v[84:87], v96 offset:40960
	v_add_u32_e32 v79, v140, v173
	ds_read_b128 v[88:91], v79
	ds_read_b128 v[96:99], v97 offset:40960
	s_waitcnt lgkmcnt(2)
	v_mfma_f32_32x32x16_bf16 v[2:17], v[92:95], v[84:87], v[2:17]
	v_mad_u64_u32 v[84:85], s[88:89], v100, s97, v[102:103]
	v_mad_i32_i24 v85, v101, s97, v85
	v_lshl_add_u64 v[84:85], v[84:85], 0, v[36:37]
	v_lshl_add_u64 v[84:85], v[84:85], 0, s[82:83]
	v_lshl_add_u64 v[86:87], v[84:85], 0, v[38:39]
	v_lshl_add_u64 v[92:93], v[84:85], 0, v[40:41]
	s_waitcnt lgkmcnt(0)
	v_mfma_f32_32x32x16_bf16 v[2:17], v[88:91], v[96:99], v[2:17]
	v_lshl_add_u64 v[94:95], v[84:85], 0, v[42:43]
	s_nop 10
	v_cndmask_b32_e64 v2, 0, v2, s[10:11]
	v_cndmask_b32_e64 v3, 0, v3, s[12:13]
	v_cndmask_b32_e64 v4, 0, v4, s[14:15]
	v_cndmask_b32_e64 v5, 0, v5, s[16:17]
	v_cndmask_b32_e64 v6, 0, v6, s[18:19]
	v_cndmask_b32_e64 v7, 0, v7, s[20:21]
	v_cndmask_b32_e64 v8, 0, v8, s[22:23]
	v_cndmask_b32_e64 v9, 0, v9, s[24:25]
	v_cndmask_b32_e64 v10, 0, v10, s[26:27]
	v_cndmask_b32_e64 v11, 0, v11, s[28:29]
	v_cndmask_b32_e64 v12, 0, v12, s[30:31]
	v_cndmask_b32_e64 v13, 0, v13, s[34:35]
	v_cvt_pk_bf16_f32 v2, v2, v3
	v_cvt_pk_bf16_f32 v3, v4, v5
	v_cndmask_b32_e64 v16, 0, v16, s[40:41]
	v_cvt_pk_bf16_f32 v4, v6, v7
	v_cvt_pk_bf16_f32 v5, v8, v9
	v_cvt_pk_bf16_f32 v6, v10, v11
	v_cvt_pk_bf16_f32 v7, v12, v13
	global_store_dwordx2 v[86:87], v[2:3], off
	global_store_dwordx2 v[92:93], v[4:5], off
	global_store_dwordx2 v[94:95], v[6:7], off
	v_cndmask_b32_e64 v2, 0, v17, s[42:43]
	v_cvt_pk_bf16_f32 v7, v16, v2
	ds_read_b128 v[2:5], v24 offset:40960
	v_cndmask_b32_e64 v14, 0, v14, s[36:37]
	v_cndmask_b32_e64 v15, 0, v15, s[38:39]
	v_cvt_pk_bf16_f32 v6, v14, v15
	v_lshl_add_u64 v[8:9], v[84:85], 0, v[44:45]
	v_mad_i64_i32 v[10:11], s[88:89], s84, v212, v[66:67]
	global_store_dwordx2 v[8:9], v[6:7], off
	ds_read_b128 v[6:9], v24 offset:57344
	s_waitcnt lgkmcnt(1)
	global_store_dwordx4 v[10:11], v[2:5], off
	ds_read_b128 v[2:5], v201 offset:40960
	v_lshl_add_u64 v[10:11], s[84:85], 0, v[46:47]
	v_mad_u64_u32 v[14:15], s[88:89], v10, s97, v[68:69]
	v_mad_i32_i24 v15, v11, s97, v15
	ds_read_b128 v[10:13], v202 offset:40960
	s_waitcnt lgkmcnt(1)
	global_store_dwordx4 v[14:15], v[2:5], off
	s_nop 1
	v_mad_i64_i32 v[2:3], s[88:89], s84, v212, v[70:71]
	global_store_dwordx4 v[2:3], v[6:9], off
	v_lshl_add_u64 v[2:3], s[84:85], 0, v[48:49]
	v_mad_u64_u32 v[4:5], s[88:89], v2, s97, v[72:73]
	v_mad_i32_i24 v5, v3, s97, v5
	s_waitcnt lgkmcnt(0)
	global_store_dwordx4 v[4:5], v[10:13], off
	ds_read_u16 v2, v205 offset:8192
	ds_read_u16 v3, v205 offset:8704
	ds_read_u16 v4, v205 offset:9216
	ds_read_u16 v5, v205 offset:9728
	ds_read_u16 v6, v205 offset:10240
	ds_read_u16 v7, v205 offset:10752
	ds_read_u16 v8, v205 offset:11264
	ds_read_u16 v9, v205 offset:11776
	ds_read_u16 v10, v206 offset:8192
	ds_read_u16 v11, v206 offset:8704
	ds_read_u16 v12, v206 offset:9216
	ds_read_u16 v13, v206 offset:9728
	ds_read_u16 v14, v206 offset:10240
	ds_read_u16 v15, v206 offset:10752
	ds_read_u16 v16, v206 offset:11264
	ds_read_u16 v17, v206 offset:11776
	s_lshl_b64 s[84:85], s[84:85], 15
	s_waitcnt lgkmcnt(14)
	v_lshl_or_b32 v2, v3, 16, v2
	s_waitcnt lgkmcnt(12)
	v_lshl_or_b32 v3, v5, 16, v4
	s_waitcnt lgkmcnt(10)
	v_lshl_or_b32 v4, v7, 16, v6
	v_lshl_add_u64 v[6:7], v[74:75], 0, s[84:85]
	s_waitcnt lgkmcnt(8)
	v_lshl_or_b32 v5, v9, 16, v8
	v_lshl_add_u64 v[8:9], v[6:7], 0, v[50:51]
	global_store_dwordx4 v[8:9], v[2:5], off
	v_lshl_add_u64 v[8:9], v[6:7], 0, v[52:53]
	s_mov_b32 s84, s71
	s_waitcnt lgkmcnt(6)
	v_lshl_or_b32 v2, v11, 16, v10
	s_waitcnt lgkmcnt(4)
	v_lshl_or_b32 v3, v13, 16, v12
	s_waitcnt lgkmcnt(2)
	v_lshl_or_b32 v4, v15, 16, v14
	s_waitcnt lgkmcnt(0)
	v_lshl_or_b32 v5, v17, 16, v16
	ds_read_u16 v10, v207 offset:8192
	ds_read_u16 v11, v207 offset:8704
	ds_read_u16 v12, v207 offset:9216
	ds_read_u16 v13, v207 offset:9728
	ds_read_u16 v14, v207 offset:10240
	ds_read_u16 v15, v207 offset:10752
	ds_read_u16 v16, v207 offset:11264
	ds_read_u16 v17, v207 offset:11776
	global_store_dwordx4 v[8:9], v[2:5], off
	v_lshl_add_u64 v[8:9], v[6:7], 0, v[54:55]
	v_lshl_add_u64 v[6:7], v[6:7], 0, v[58:59]
	s_waitcnt lgkmcnt(6)
	v_lshl_or_b32 v2, v11, 16, v10
	s_waitcnt lgkmcnt(4)
	v_lshl_or_b32 v3, v13, 16, v12
	s_waitcnt lgkmcnt(2)
	v_lshl_or_b32 v4, v15, 16, v14
	s_waitcnt lgkmcnt(0)
	v_lshl_or_b32 v5, v17, 16, v16
	ds_read_u16 v10, v208 offset:8192
	ds_read_u16 v11, v208 offset:8704
	ds_read_u16 v12, v208 offset:9216
	ds_read_u16 v13, v208 offset:9728
	ds_read_u16 v14, v208 offset:10240
	ds_read_u16 v15, v208 offset:10752
	ds_read_u16 v16, v208 offset:11264
	ds_read_u16 v17, v208 offset:11776
	global_store_dwordx4 v[8:9], v[2:5], off
	s_waitcnt lgkmcnt(6)
	s_nop 0
	v_lshl_or_b32 v2, v11, 16, v10
	s_waitcnt lgkmcnt(4)
	v_lshl_or_b32 v3, v13, 16, v12
	s_waitcnt lgkmcnt(2)
	v_lshl_or_b32 v4, v15, 16, v14
	s_waitcnt lgkmcnt(0)
	v_lshl_or_b32 v5, v17, 16, v16
	global_store_dwordx4 v[6:7], v[2:5], off
	v_add_u32_e32 v205, s67, v205
	v_add_u32_e32 v206, s67, v206
	v_add_u32_e32 v207, s67, v207
	v_add_u32_e32 v208, s67, v208
	s_sub_i32 s67, 0, s67
	s_xor_b32 s66, s66, 0x1c000
	s_cbranch_vccnz .LBB0_350

; #define LAS __attribute__((address_space(3)))
; #define PP_FETCH(task_) do { const int c_ = (task_) >> 2, h_ = (task_) & 3; const size_t t0_ = (size_t)c_ * 64; \
;         n_lr = *(const f32x4*)(LR + t0_ * 32 + tid * 4); \
;         _Pragma("unroll") for (int r_ = 0; r_ < 8; ++r_) { const bf16_t* rp_ = PG + (t0_ + rg * 8 + r_) * 2048 + h_ * 128 + c0; n_q[r_] = *(const unsigned*)rp_; n_k[r_] = *(const unsigned*)(rp_ + 512); } } while (0)
; DI void phase_gla_prep(const Params& P, int l, int bid, int nb, LAS unsigned char* lds) {
;     ...
;         __syncthreads();
;         if (h != hcur) { hcur = h;
;             for (int e = tid; e < 2 * 16 * 128; e += NTHR) { const int dir = e >> 11, k = (e >> 7) & 15, cc = e & 127;
;                 ((LAS float*)(lds + PP_W))[e] = (dir ? P.w_gk_b : P.w_gk_f)[(size_t)l * 16 * 512 + k * 512 + h * 128 + cc]; }
;             bbs[0] = *(const f32x2*)(P.b_gk_f + l * 512 + h * 128 + c0); bbs[1] = *(const f32x2*)(P.b_gk_b + l * 512 + h * 128 + c0); }
;         *(LAS f32x4*)(lds + PP_LR + tid * 16) = n_lr;
;         unsigned qw[8], kw[8];
; #pragma unroll
;         for (int r = 0; r < 8; ++r) { qw[r] = n_q[r]; kw[r] = n_k[r]; }
;         asm volatile("" : "+v"(qw[0]), "+v"(qw[1]), "+v"(qw[2]), "+v"(qw[3]), "+v"(qw[4]), "+v"(qw[5]), "+v"(qw[6]), "+v"(qw[7]), "+v"(kw[0]), "+v"(kw[1]), "+v"(kw[2]), "+v"(kw[3]), "+v"(kw[4]), "+v"(kw[5]), "+v"(kw[6]), "+v"(kw[7]) :: "memory");
;         __builtin_amdgcn_sched_barrier(0);
;         { const int wu = __builtin_amdgcn_readfirstlane(wid);
; #pragma unroll
;           for (int q = 0; q < 4; ++q) { const int row = wu * 8 + q * 2 + (lane >> 5);
;               __builtin_amdgcn_global_load_lds((const unsigned*)(PG + ((size_t)c * 64 + row) * 2048 + 1024 + h * 256 + (lane & 31) * 8), (LAS unsigned*)(lds + PP_V + (wu * 8 + q * 2) * 512), 16, 0, 0); } }
;         if (task + nb < 2560) PP_FETCH(task + nb);
;         asm volatile("s_waitcnt lgkmcnt(0)" ::: "memory"); __builtin_amdgcn_s_barrier(); asm volatile("" ::: "memory");
.LBB0_339:
	s_or_b64 exec, exec, s[86:87]
	s_lshl_b32 s76, s70, 2
	v_lshl_add_u64 v[2:3], v[60:61], 0, s[76:77]
	global_load_dwordx2 v[80:81], v[2:3], off
	v_lshl_add_u64 v[2:3], v[62:63], 0, s[76:77]
	global_load_dwordx2 v[82:83], v[2:3], off
	s_waitcnt vmcnt(0)
	s_mov_b32 s70, s71
.LBB0_340:
	v_add_u32_e32 v24, 0, v22
	ds_write_b128 v24, v[18:21]
	v_mov_b32_e32 v14, v179
	v_mov_b32_e32 v2, v214
	v_mov_b32_e32 v9, v185
	v_mov_b32_e32 v11, v177
	v_mov_b32_e32 v5, v193
	v_mov_b32_e32 v7, v187
	v_mov_b32_e32 v16, v178
	v_mov_b32_e32 v3, v213
	v_mov_b32_e32 v4, v200
	v_mov_b32_e32 v13, v176
	v_mov_b32_e32 v15, v192
	v_mov_b32_e32 v10, v186
	v_mov_b32_e32 v12, v196
	v_mov_b32_e32 v6, v199
	v_mov_b32_e32 v8, v209
	v_mov_b32_e32 v17, v174
	s_add_i32 s71, s84, s94
	s_cmpk_gt_i32 s71, 0x9ff
	s_cselect_b64 s[86:87], -1, 0
	s_and_b64 vcc, exec, s[86:87]
	s_cbranch_vccnz .LBB0_342
	s_ashr_i32 s88, s71, 2
	s_lshl_b32 s76, s71, 8
	s_ashr_i32 s89, s88, 31
	s_and_b32 s76, s76, 0x300
	s_lshl_b64 s[90:91], s[88:89], 13
	v_lshl_add_u64 v[20:21], v[28:29], 0, s[76:77]
	s_lshl_b64 s[88:89], s[88:89], 18
	v_lshl_add_u64 v[20:21], v[20:21], 0, s[88:89]
	v_lshl_add_u64 v[84:85], v[20:21], 0, v[56:57]
	v_add_co_u32_e32 v86, vcc, 0x1000, v84
	v_lshl_add_u64 v[18:19], v[26:27], 0, s[90:91]
	s_nop 0
	v_addc_co_u32_e32 v87, vcc, 0, v85, vcc
	v_add_co_u32_e32 v88, vcc, 0x2000, v84
	global_load_dwordx4 v[18:21], v[18:19], off
	s_nop 0
	global_load_dword v178, v[84:85], off
	global_load_dword v179, v[84:85], off offset:1024
	global_load_dword v174, v[86:87], off
	v_addc_co_u32_e32 v89, vcc, 0, v85, vcc
	v_add_co_u32_e32 v90, vcc, 0x3000, v84
	s_nop 1
	v_addc_co_u32_e32 v91, vcc, 0, v85, vcc
	v_add_co_u32_e32 v92, vcc, 0x4000, v84
	s_nop 1
	v_addc_co_u32_e32 v93, vcc, 0, v85, vcc
	v_add_co_u32_e32 v94, vcc, 0x5000, v84
	s_nop 1
	v_addc_co_u32_e32 v95, vcc, 0, v85, vcc
	global_load_dword v192, v[86:87], off offset:1024
	global_load_dword v176, v[88:89], off
	global_load_dword v177, v[88:89], off offset:1024
	global_load_dword v185, v[90:91], off
	global_load_dword v196, v[90:91], off offset:1024
	global_load_dword v186, v[92:93], off
	global_load_dword v187, v[92:93], off offset:1024
	global_load_dword v193, v[94:95], off
	v_add_co_u32_e32 v86, vcc, 0x6000, v84
	s_nop 1
	v_addc_co_u32_e32 v87, vcc, 0, v85, vcc
	v_add_co_u32_e32 v84, vcc, 0x7000, v84
	s_nop 1
	v_addc_co_u32_e32 v85, vcc, 0, v85, vcc
	global_load_dword v209, v[94:95], off offset:1024
	global_load_dword v199, v[86:87], off
	global_load_dword v200, v[86:87], off offset:1024
	global_load_dword v213, v[84:85], off
	global_load_dword v214, v[84:85], off offset:1024
	s_ashr_i32 s68, s71, 2
	s_ashr_i32 s69, s68, 31
	s_lshl_b64 s[68:69], s[68:69], 18
	s_add_u32 s68, s74, s68
	s_addc_u32 s69, s75, s69
	s_add_u32 s68, s68, s78
	s_addc_u32 s69, s69, s79
	s_and_b32 s32, s71, 3
	s_lshl_b32 s32, s32, 9
	s_add_u32 s68, s68, s32
	s_addc_u32 s69, s69, 0
	v_readfirstlane_b32 s95, v137
	s_lshl_b32 s32, s95, 12
	s_add_i32 s32, s32, s66
	s_addk_i32 s32, 0x2000
	s_lshl_b32 s95, s95, 3
	v_or_b32_e32 v85, s95, v139
	v_lshl_add_u32 v85, v85, 12, v78
	s_mov_b32 m0, s32
	s_nop 0
	global_load_lds_dwordx4 v85, s[68:69]
	v_add_u32_e32 v84, 0x2000, v85
	s_add_i32 m0, s32, 0x400
	s_nop 0
	global_load_lds_dwordx4 v84, s[68:69]
	v_add_u32_e32 v84, 0x4000, v85
	s_add_i32 m0, s32, 0x800
	s_nop 0
	global_load_lds_dwordx4 v84, s[68:69]
	v_add_u32_e32 v84, 0x6000, v85
	s_add_i32 m0, s32, 0xc00
	s_nop 0
	global_load_lds_dwordx4 v84, s[68:69]
.LBB0_342:
	v_lshlrev_b32_e32 v114, 16, v2
	v_and_b32_e32 v115, 0xffff0000, v2
	v_and_b32_e32 v2, 63, v210
	v_cmp_gt_u32_e32 vcc, 56, v2
	v_lshlrev_b32_e32 v112, 16, v3
	v_and_b32_e32 v113, 0xffff0000, v3
	v_cndmask_b32_e64 v3, 0, 8, vcc
	v_cmp_gt_u32_e32 vcc, 48, v2
	v_add_lshl_u32 v79, v3, v210, 2
	s_waitcnt lgkmcnt(0)
	s_barrier
	v_cndmask_b32_e64 v2, 0, 16, vcc
	v_add_lshl_u32 v215, v2, v210, 2
	v_and_b32_e32 v2, 64, v210
	v_or_b32_e32 v3, v2, v138
	v_lshlrev_b32_e32 v216, 2, v3
	v_add_u32_e32 v3, -8, v210
	v_cmp_lt_i32_e32 vcc, v3, v2
	s_ashr_i32 s85, s84, 31
	v_lshlrev_b32_e32 v84, 16, v16
	v_cndmask_b32_e32 v3, v3, v210, vcc
	v_lshlrev_b32_e32 v217, 2, v3
	v_add_u32_e32 v3, -16, v210
	v_cmp_lt_i32_e32 vcc, v3, v2
	v_and_b32_e32 v85, 0xffff0000, v16
	v_lshlrev_b32_e32 v86, 16, v14
	v_cndmask_b32_e32 v3, v3, v210, vcc
	v_lshlrev_b32_e32 v218, 2, v3
	v_subrev_u32_e32 v3, 32, v210
	v_cmp_lt_i32_e32 vcc, v3, v2
	v_and_b32_e32 v87, 0xffff0000, v14
	v_lshlrev_b32_e32 v88, 16, v17
	v_cndmask_b32_e32 v2, v3, v210, vcc
	v_and_b32_e32 v89, 0xffff0000, v17
	v_lshlrev_b32_e32 v90, 16, v15
	v_and_b32_e32 v91, 0xffff0000, v15
	v_lshlrev_b32_e32 v92, 16, v13
	v_and_b32_e32 v93, 0xffff0000, v13
	v_lshlrev_b32_e32 v94, 16, v11
	v_and_b32_e32 v95, 0xffff0000, v11
	v_lshlrev_b32_e32 v96, 16, v9
	v_and_b32_e32 v97, 0xffff0000, v9
	v_lshlrev_b32_e32 v98, 16, v12
	v_and_b32_e32 v99, 0xffff0000, v12
	v_lshlrev_b32_e32 v100, 16, v10
	v_and_b32_e32 v101, 0xffff0000, v10
	v_lshlrev_b32_e32 v102, 16, v7
	v_and_b32_e32 v103, 0xffff0000, v7
	v_lshlrev_b32_e32 v104, 16, v5
	v_and_b32_e32 v105, 0xffff0000, v5
	v_lshlrev_b32_e32 v106, 16, v8
	v_and_b32_e32 v107, 0xffff0000, v8
	v_lshlrev_b32_e32 v108, 16, v6
	v_and_b32_e32 v109, 0xffff0000, v6
	v_lshlrev_b32_e32 v110, 16, v4
	v_and_b32_e32 v111, 0xffff0000, v4
	s_mov_b32 s76, 0
	v_lshlrev_b32_e32 v219, 2, v2
	v_or_b32_e32 v220, 0xe0, v216
	s_mov_b64 s[88:89], -1
	s_branch .LBB0_344

; #define LAS __attribute__((address_space(3)))
; #define PP_FETCH(task_) do { const int c_ = (task_) >> 2, h_ = (task_) & 3; const size_t t0_ = (size_t)c_ * 64; \
;         n_lr = *(const f32x4*)(LR + t0_ * 32 + tid * 4); \
;         _Pragma("unroll") for (int r_ = 0; r_ < 8; ++r_) { const bf16_t* rp_ = PG + (t0_ + rg * 8 + r_) * 2048 + h_ * 128 + c0; n_q[r_] = *(const unsigned*)rp_; n_k[r_] = *(const unsigned*)(rp_ + 512); } } while (0)
; DI void phase_gla_prep(const Params& P, int l, int bid, int nb, LAS unsigned char* lds) {
;     const int tid = threadIdx.x, wid = tid >> 6, lane = tid & 63, dpl = lane & 7, rg = lane >> 3, r32 = lane & 31, hi = lane >> 5;
;     const bf16_t* PG = (const bf16_t*)(P.ws + WS_PG); const float* LR = (const float*)(P.ws + WS_LR);
;     const int c0 = wid * 16 + dpl * 2;
;     const int p0 = (c0 & ~15) | (c0 & 3) | ((c0 & 4) << 1) | ((c0 & 8) >> 1);
;     int hcur = -1;
;     f32x4 n_lr; unsigned n_q[8], n_k[8];
;     ...
;     if (bid < 2560) PP_FETCH(bid);
;     ...
;         { const int dir = wid >> 2, ti = (wid >> 1) & 1, tj = wid & 1; const int i = ti * 32 + r32, jr = tj * 32 + r32;
;           f32x16 acc; for (int x = 0; x < 16; ++x) acc[x] = 0.f;
; #pragma unroll
;           for (int s = 0; s < 8; ++s) { const int ch = 2 * s + hi;
;               const bf16x8 a = *(const LAS bf16x8*)(lds + PP_KD + dir * 16384 + jr * 256 + ((ch ^ (jr & 15)) << 4));
;               const bf16x8 b = *(const LAS bf16x8*)(lds + PP_QD + dir * 16384 + i * 256 + ((ch ^ (i & 15)) << 4));
;               acc = __builtin_amdgcn_mfma_f32_32x32x16_bf16(a, b, acc, 0, 0, 0); }
;           unsigned char* am = P.ws + GL_PD + ((size_t)dir * 2560 + task) * GL_PD_BYTES + 16384;
; #pragma unroll
;           for (int a4 = 0; a4 < 4; ++a4) { float v[4];
; #pragma unroll
;               for (int b4 = 0; b4 < 4; ++b4) { const int j = tj * 32 + 8 * a4 + 4 * hi + b4; const bool keep = dir ? (j >= i) : (j <= i); v[b4] = keep ? acc[a4 * 4 + b4] : 0.f; }
.LBB0_894:
	s_cmp_lt_i32 s72, 9
	s_cselect_b64 s[0:1], -1, 0
	s_cmp_gt_i32 s73, 8
	s_cselect_b64 s[2:3], -1, 0
	s_and_b64 s[0:1], s[0:1], s[2:3]
	s_andn2_b64 vcc, exec, s[0:1]
	s_cbranch_vccnz .LBB0_962
	s_cmpk_gt_i32 s33, 0x9ff
	v_and_b32_e32 v136, 0x3ff, v0
	s_cbranch_scc1 .LBB0_912
	v_lshrrev_b32_e32 v137, 6, v136
	v_and_b32_e32 v138, 7, v136
	v_lshlrev_b32_e32 v3, 2, v136
	v_lshlrev_b32_e32 v2, 4, v137
	v_and_or_b32 v4, v3, 8, v2
	v_lshlrev_b32_e32 v5, 1, v138
	v_and_b32_e32 v6, 4, v136
	v_bfe_u32 v9, v136, 3, 3
	v_and_or_b32 v6, v5, 2, v6
	v_lshrrev_b32_e32 v10, 3, v4
	v_bitop3_b32 v4, v9, v136, 7 bitop3:0x78
	s_add_u32 s74, s50, 0x10440000
	v_or_b32_e32 v8, v2, v5
	v_and_b32_e32 v5, 31, v136
	v_lshlrev_b32_e32 v11, 1, v6
	v_lshlrev_b32_e32 v32, 4, v4
	v_bfe_u32 v4, v136, 6, 1
	v_lshrrev_b32_e32 v6, 2, v136
	s_addc_u32 s75, s51, 0
	v_and_or_b32 v9, v6, 32, v5
	v_lshlrev_b32_e32 v6, 5, v4
	s_add_u32 s44, s50, 0x1f440000
	v_lshlrev_b32_e32 v2, 3, v5
	v_lshrrev_b32_e32 v12, 8, v136
	v_or_b32_e32 v5, v6, v5
	s_addc_u32 s45, s51, 0
	v_lshlrev_b32_e32 v13, 14, v12
	s_add_i32 s2, 0, 0x12000
	v_lshlrev_b32_e32 v5, 8, v5
	v_bfe_u32 v139, v136, 5, 1
	v_add3_u32 v140, s2, v13, v5
	v_lshlrev_b32_e32 v5, 8, v9
	v_add3_u32 v141, 0, v13, v5
	v_lshl_or_b32 v13, v139, 2, v6
	v_lshlrev_b32_e32 v6, 2, v8
	s_add_i32 s2, 0, 0x1a200
	v_add_u32_e32 v143, s2, v6
	s_add_i32 s2, 0, 0x1a400
	v_add_u32_e32 v144, s2, v6
	s_add_i32 s2, 0, 0x1a600
	v_add_u32_e32 v145, s2, v6
	s_add_i32 s2, 0, 0x1a800
	v_add_u32_e32 v147, s2, v6
	s_add_i32 s2, 0, 0x1aa00
	v_add_u32_e32 v148, s2, v6
	s_add_i32 s2, 0, 0x1ac00
	v_add_u32_e32 v149, s2, v6
	s_add_i32 s2, 0, 0x1ae00
	v_add_u32_e32 v150, s2, v6
	s_add_i32 s2, 0, 0x1b000
	v_add_u32_e32 v151, s2, v6
	s_add_i32 s2, 0, 0x1b200
	v_add_u32_e32 v152, s2, v6
	s_add_i32 s2, 0, 0x1b400
	v_add_u32_e32 v153, s2, v6
	s_add_i32 s2, 0, 0x1b600
	v_add_u32_e32 v154, s2, v6
	s_add_i32 s2, 0, 0x1b800
	v_add_u32_e32 v155, s2, v6
	s_add_i32 s2, 0, 0x1ba00
	v_add_u32_e32 v156, s2, v6
	s_add_i32 s2, 0, 0x1bc00
	s_waitcnt lgkmcnt(0)
	v_and_b32_e32 v7, 63, v136
	v_and_b32_e32 v64, 56, v136
	v_add_u32_e32 v157, s2, v6
	s_add_i32 s2, 0, 0x1be00
	v_lshlrev_b32_e32 v24, 1, v8
	v_lshlrev_b32_e32 v30, 7, v8
	v_cmp_gt_u32_e64 s[0:1], 8, v7
	v_add_u32_e32 v158, s2, v6
	v_cmp_gt_u32_e64 s[2:3], 56, v7
	v_cmp_gt_u32_e64 s[4:5], 48, v7
	v_cmp_gt_u32_e64 s[6:7], 32, v7
	v_cmp_gt_u32_e64 s[8:9], 16, v7
	v_bitop3_b32 v7, v10, v136, 8 bitop3:0x78
	v_lshl_or_b32 v8, v64, 8, v11
	v_lshl_add_u32 v159, v7, 4, v8
	v_or_b32_e32 v7, 1, v64
	v_bitop3_b32 v8, v10, v7, 9 bitop3:0x78
	v_lshl_or_b32 v7, v7, 8, v11
	v_lshl_add_u32 v160, v8, 4, v7
	v_or_b32_e32 v7, 2, v64
	v_bitop3_b32 v8, v10, v7, 10 bitop3:0x78
	v_lshl_or_b32 v7, v7, 8, v11
	v_lshl_add_u32 v162, v8, 4, v7
	v_or_b32_e32 v7, 3, v64
	v_bitop3_b32 v8, v10, v7, 11 bitop3:0x78
	v_lshl_or_b32 v7, v7, 8, v11
	v_lshl_add_u32 v164, v8, 4, v7
	v_or_b32_e32 v7, 4, v64
	v_bitop3_b32 v8, v10, v7, 12 bitop3:0x78
	v_lshl_or_b32 v7, v7, 8, v11
	v_lshl_add_u32 v165, v8, 4, v7
	v_or_b32_e32 v7, 5, v64
	v_bitop3_b32 v8, v10, v7, 13 bitop3:0x78
	v_lshl_or_b32 v7, v7, 8, v11
	v_lshl_add_u32 v166, v8, 4, v7
	v_or_b32_e32 v7, 6, v64
	v_bitop3_b32 v8, v10, v7, 14 bitop3:0x78
	v_lshl_or_b32 v7, v7, 8, v11
	v_lshl_add_u32 v167, v8, 4, v7
	v_or_b32_e32 v7, 7, v64
	v_bitop3_b32 v8, v10, v7, 15 bitop3:0x78
	v_lshl_or_b32 v7, v7, 8, v11
	v_and_b32_e32 v14, 15, v136
	v_lshl_add_u32 v168, v8, 4, v7
	v_bitop3_b32 v7, v139, v136, 15 bitop3:0x78
	v_lshlrev_b32_e32 v169, 4, v7
	v_bitop3_b32 v7, v139, v14, 2 bitop3:0x36
	v_lshlrev_b32_e32 v170, 4, v7
	v_bitop3_b32 v7, v139, v14, 4 bitop3:0x36
	v_lshlrev_b32_e32 v171, 4, v7
	v_bitop3_b32 v7, v139, v14, 6 bitop3:0x36
	v_lshlrev_b32_e32 v172, 4, v7
	v_bitop3_b32 v7, v139, v14, 8 bitop3:0x36
	v_lshlrev_b32_e32 v173, 4, v7
	v_bitop3_b32 v7, v139, v14, 10 bitop3:0x36
	v_lshlrev_b32_e32 v174, 4, v7
	v_bitop3_b32 v7, v139, v14, 12 bitop3:0x36
	v_lshlrev_b32_e32 v175, 4, v7
	v_bitop3_b32 v7, v139, v14, 14 bitop3:0x36
	v_cmp_le_u32_e32 vcc, v13, v9
	s_movk_i32 s10, 0x100
	v_lshlrev_b32_e32 v176, 4, v7
	v_cndmask_b32_e64 v7, 0, 1, vcc
	v_cmp_ge_u32_e32 vcc, v13, v9
	v_cmp_lt_u32_e64 s[12:13], v13, v9
	v_lshlrev_b32_e32 v15, 2, v4
	v_cndmask_b32_e64 v8, 0, 1, vcc
	v_cmp_gt_u32_e32 vcc, s10, v136
	v_lshrrev_b32_e32 v65, 1, v136
	v_lshlrev_b32_e32 v17, 3, v139
	v_cndmask_b32_e32 v7, v8, v7, vcc
	v_and_b32_e32 v7, 1, v7
	v_cmp_eq_u32_e64 s[10:11], 1, v7
	v_or_b32_e32 v7, 1, v13
	v_cndmask_b32_e64 v8, 0, 1, s[12:13]
	v_cmp_ge_u32_e64 s[12:13], v7, v9
	v_bfe_u32 v16, v136, 1, 3
	v_add_u32_e32 v76, 0x200, v136
	v_cndmask_b32_e64 v7, 0, 1, s[12:13]
	v_cndmask_b32_e32 v7, v7, v8, vcc
	v_and_b32_e32 v7, 1, v7
	v_cmp_eq_u32_e64 s[12:13], 1, v7
	v_or_b32_e32 v7, 2, v13
	v_cmp_le_u32_e64 s[14:15], v7, v9
	s_add_i32 s70, 0, 0x1a000
	v_add_u32_e32 v81, 0x600, v136
	v_cndmask_b32_e64 v8, 0, 1, s[14:15]
	v_cmp_ge_u32_e64 s[14:15], v7, v9
	s_add_u32 s78, s50, 0x29e70000
	s_addc_u32 s79, s51, 0
	v_cndmask_b32_e64 v7, 0, 1, s[14:15]
	v_cndmask_b32_e32 v7, v7, v8, vcc
	v_and_b32_e32 v7, 1, v7
	v_cmp_eq_u32_e64 s[14:15], 1, v7
	v_or_b32_e32 v7, 3, v13
	v_cmp_le_u32_e64 s[16:17], v7, v9
	s_lshl_b32 s65, s33, 8
	s_and_b32 s65, s65, 0x300
	v_cndmask_b32_e64 v8, 0, 1, s[16:17]
	v_cmp_ge_u32_e64 s[16:17], v7, v9
	s_add_u32 s80, s74, s65
	v_mov_b32_e32 v25, 0
	v_cndmask_b32_e64 v7, 0, 1, s[16:17]
	v_cndmask_b32_e32 v7, v7, v8, vcc
	v_and_b32_e32 v7, 1, v7
	v_cmp_eq_u32_e64 s[16:17], 1, v7
	v_bitop3_b32 v7, v15, v65, 7 bitop3:0x78
	v_lshl_or_b32 v38, v7, 4, v17
	v_or_b32_e32 v7, 8, v13
	v_cmp_le_u32_e64 s[18:19], v7, v9
; DI void phase_gla_prep(const Params& P, int l, int bid, int nb, LAS unsigned char* lds) {
;     const int tid = threadIdx.x, wid = tid >> 6, lane = tid & 63, dpl = lane & 7, rg = lane >> 3, r32 = lane & 31, hi = lane >> 5;
;     const bf16_t* PG = (const bf16_t*)(P.ws + WS_PG); const float* LR = (const float*)(P.ws + WS_LR);
;     const int c0 = wid * 16 + dpl * 2;
;     const int p0 = (c0 & ~15) | (c0 & 3) | ((c0 & 4) << 1) | ((c0 & 8) >> 1);
;     int hcur = -1;
;     f32x4 n_lr; unsigned n_q[8], n_k[8];
;     ...
;     if (bid < 2560) PP_FETCH(bid);
;     ...
;             unsigned char* pd = P.ws + GL_PD + ((size_t)dir * 2560 + task) * GL_PD_BYTES;
;             { const int dA = c0, dB = c0 + 1;
;               *(u32x4*)(pd + 24576 + dA * 128 + ((rg ^ ((dA >> 1) & 7)) << 4)) = (u32x4){kt0[0], kt0[1], kt0[2], kt0[3]};
;               *(u32x4*)(pd + 24576 + dB * 128 + ((rg ^ ((dB >> 1) & 7)) << 4)) = (u32x4){kt1[0], kt1[1], kt1[2], kt1[3]}; }
;             if (rg == 0) { float* dec = (float*)(P.ws + GL_DEC) + ((size_t)dir * 2560 + task) * 128; *(f32x2*)(dec + c0) = (f32x2){d0, d1}; }
;         }
;         __syncthreads();
;         { const int dir = wid >> 2, ti = (wid >> 1) & 1, tj = wid & 1; const int i = ti * 32 + r32, jr = tj * 32 + r32;
;           f32x16 acc; for (int x = 0; x < 16; ++x) acc[x] = 0.f;
; #pragma unroll
;           for (int s = 0; s < 8; ++s) { const int ch = 2 * s + hi;
;               const bf16x8 a = *(const LAS bf16x8*)(lds + PP_KD + dir * 16384 + jr * 256 + ((ch ^ (jr & 15)) << 4));
;               const bf16x8 b = *(const LAS bf16x8*)(lds + PP_QD + dir * 16384 + i * 256 + ((ch ^ (i & 15)) << 4));
;               acc = __builtin_amdgcn_mfma_f32_32x32x16_bf16(a, b, acc, 0, 0, 0); }
;           unsigned char* am = P.ws + GL_PD + ((size_t)dir * 2560 + task) * GL_PD_BYTES + 16384;
; #pragma unroll
;           for (int a4 = 0; a4 < 4; ++a4) { float v[4];
; #pragma unroll
;               for (int b4 = 0; b4 < 4; ++b4) { const int j = tj * 32 + 8 * a4 + 4 * hi + b4; const bool keep = dir ? (j >= i) : (j <= i); v[b4] = keep ? acc[a4 * 4 + b4] : 0.f; }
;               u32x2 w; w.x = pkbf(v[0], v[1]); w.y = pkbf(v[2], v[3]);
;               *(u32x2*)(am + i * 128 + ((((4 * tj + a4) ^ ((i >> 1) & 7)) << 4) | (hi << 3))) = w; } }
; #pragma unroll
;         for (int q = 0; q < 4; ++q) { const int e = q * 512 + tid, dir = e >> 10, o = (e & 1023) * 16;
	s_addc_u32 s81, s75, 0
	v_mul_u32_u24_e32 v34, 0xa00, v12
	v_cndmask_b32_e64 v8, 0, 1, s[18:19]
	v_cmp_ge_u32_e64 s[18:19], v7, v9
	v_lshlrev_b32_e32 v83, 12, v12
	v_lshlrev_b32_e32 v56, 12, v64
	v_cndmask_b32_e64 v7, 0, 1, s[18:19]
	v_cndmask_b32_e32 v7, v7, v8, vcc
	v_and_b32_e32 v7, 1, v7
	v_cmp_eq_u32_e64 s[18:19], 1, v7
	v_or_b32_e32 v7, 9, v13
	v_cmp_le_u32_e64 s[20:21], v7, v9
	v_mov_b32_e32 v57, v25
	s_movk_i32 s65, 0x1000
	v_cndmask_b32_e64 v8, 0, 1, s[20:21]
	v_cmp_ge_u32_e64 s[20:21], v7, v9
	v_lshlrev_b32_e32 v22, 4, v136
	v_mov_b32_e32 v23, v25
	v_cndmask_b32_e64 v7, 0, 1, s[20:21]
	v_cndmask_b32_e32 v7, v7, v8, vcc
	v_and_b32_e32 v7, 1, v7
	v_cmp_eq_u32_e64 s[20:21], 1, v7
	v_or_b32_e32 v7, 10, v13
	v_cmp_le_u32_e64 s[22:23], v7, v9
	v_lshl_add_u64 v[26:27], s[44:45], 0, v[22:23]
	v_and_b32_e32 v4, 0xff, v136
	v_cndmask_b32_e64 v8, 0, 1, s[22:23]
	v_cmp_ge_u32_e64 s[22:23], v7, v9
	v_add_u32_e32 v142, s70, v6
	v_lshl_add_u32 v79, v4, 1, 0
	v_cndmask_b32_e64 v7, 0, 1, s[22:23]
	v_cndmask_b32_e32 v7, v7, v8, vcc
	v_and_b32_e32 v7, 1, v7
	v_cmp_eq_u32_e64 s[22:23], 1, v7
	v_or_b32_e32 v7, 11, v13
	v_cmp_le_u32_e64 s[24:25], v7, v9
	v_lshlrev_b32_e32 v4, 7, v4
	v_mov_b32_e32 v5, v25
	v_cndmask_b32_e64 v8, 0, 1, s[24:25]
	v_cmp_ge_u32_e64 s[24:25], v7, v9
	v_lshl_add_u32 v178, v64, 7, 0
	v_lshl_add_u64 v[4:5], s[50:51], 0, v[4:5]
	v_cndmask_b32_e64 v7, 0, 1, s[24:25]
	v_cndmask_b32_e32 v7, v7, v8, vcc
	v_and_b32_e32 v7, 1, v7
	v_cmp_eq_u32_e64 s[24:25], 1, v7
	v_bitop3_b32 v7, v15, v16, 1 bitop3:0x36
	v_lshl_or_b32 v40, v7, 4, v17
	v_or_b32_e32 v7, 16, v13
	v_cmp_le_u32_e64 s[26:27], v7, v9
	v_and_b32_e32 v78, 0x7f, v136
	s_movk_i32 s64, 0x200
	v_cndmask_b32_e64 v8, 0, 1, s[26:27]
	v_cmp_ge_u32_e64 s[26:27], v7, v9
	v_lshl_add_u64 v[66:67], s[78:79], 0, v[22:23]
	v_add_u32_e32 v183, s70, v3
	v_cndmask_b32_e64 v7, 0, 1, s[26:27]
	v_cndmask_b32_e32 v7, v7, v8, vcc
	v_and_b32_e32 v7, 1, v7
	v_cmp_eq_u32_e64 s[26:27], 1, v7
	v_or_b32_e32 v7, 17, v13
	v_cmp_le_u32_e64 s[28:29], v7, v9
	v_lshlrev_b32_e32 v10, 4, v81
	v_lshl_add_u64 v[28:29], s[74:75], 0, v[24:25]
	v_cndmask_b32_e64 v8, 0, 1, s[28:29]
	v_cmp_ge_u32_e64 s[28:29], v7, v9
	v_lshlrev_b32_e32 v36, 7, v9
	v_and_b32_e32 v10, 0x3ff0, v10
	v_cndmask_b32_e64 v7, 0, 1, s[28:29]
	v_cndmask_b32_e32 v7, v7, v8, vcc
	v_and_b32_e32 v7, 1, v7
	v_cmp_eq_u32_e64 s[28:29], 1, v7
	v_or_b32_e32 v7, 18, v13
	v_cmp_le_u32_e64 s[30:31], v7, v9
	v_mov_b32_e32 v11, v25
	s_mov_b32 s77, 0
	v_cndmask_b32_e64 v8, 0, 1, s[30:31]
	v_cmp_ge_u32_e64 s[30:31], v7, v9
	v_mov_b32_e32 v31, v25
	v_mov_b32_e32 v33, v25
	v_cndmask_b32_e64 v7, 0, 1, s[30:31]
	v_cndmask_b32_e32 v7, v7, v8, vcc
	v_and_b32_e32 v7, 1, v7
	v_cmp_eq_u32_e64 s[30:31], 1, v7
	v_or_b32_e32 v7, 19, v13
	v_cmp_le_u32_e64 s[34:35], v7, v9
	v_mov_b32_e32 v35, v25
	v_mov_b32_e32 v37, v25
	v_cndmask_b32_e64 v8, 0, 1, s[34:35]
	v_cmp_ge_u32_e64 s[34:35], v7, v9
	v_mov_b32_e32 v39, v25
	v_mov_b32_e32 v41, v25
	v_cndmask_b32_e64 v7, 0, 1, s[34:35]
	v_cndmask_b32_e32 v7, v7, v8, vcc
	v_and_b32_e32 v7, 1, v7
	v_cmp_eq_u32_e64 s[34:35], 1, v7
	v_bitop3_b32 v7, v15, v16, 2 bitop3:0x36
	v_lshl_or_b32 v42, v7, 4, v17
	v_or_b32_e32 v7, 24, v13
	v_cmp_le_u32_e64 s[36:37], v7, v9
	v_mov_b32_e32 v43, v25
	v_mov_b32_e32 v45, v25
	v_cndmask_b32_e64 v8, 0, 1, s[36:37]
	v_cmp_ge_u32_e64 s[36:37], v7, v9
	v_mov_b32_e32 v47, v25
	v_mov_b32_e32 v49, v25
	v_cndmask_b32_e64 v7, 0, 1, s[36:37]
	v_cndmask_b32_e32 v7, v7, v8, vcc
	v_and_b32_e32 v7, 1, v7
	v_cmp_eq_u32_e64 s[36:37], 1, v7
	v_or_b32_e32 v7, 25, v13
	v_cmp_le_u32_e64 s[38:39], v7, v9
	v_mov_b32_e32 v51, v25
	v_mov_b32_e32 v53, v25
	v_cndmask_b32_e64 v8, 0, 1, s[38:39]
	v_cmp_ge_u32_e64 s[38:39], v7, v9
	v_mov_b32_e32 v55, v25
	v_lshl_add_u64 v[72:73], s[78:79], 0, v[10:11]
	v_cndmask_b32_e64 v7, 0, 1, s[38:39]
	v_cndmask_b32_e32 v7, v7, v8, vcc
	v_and_b32_e32 v7, 1, v7
	v_cmp_eq_u32_e64 s[38:39], 1, v7
	v_or_b32_e32 v7, 26, v13
	v_cmp_le_u32_e64 s[40:41], v7, v9
	s_mov_b32 s90, 0xbfb8aa3b
	s_mov_b32 s91, 0xa000
	v_cndmask_b32_e64 v8, 0, 1, s[40:41]
	v_cmp_ge_u32_e64 s[40:41], v7, v9
	v_add_u32_e32 v208, v79, v83
	v_mov_b32_e32 v215, 0xa000
	v_cndmask_b32_e64 v7, 0, 1, s[40:41]
	v_cndmask_b32_e32 v7, v7, v8, vcc
	v_and_b32_e32 v7, 1, v7
	v_cmp_eq_u32_e64 s[40:41], 1, v7
	v_or_b32_e32 v7, 27, v13
	v_cmp_le_u32_e64 s[42:43], v7, v9
	s_nop 1
	v_cndmask_b32_e64 v8, 0, 1, s[42:43]
	v_cmp_ge_u32_e64 s[42:43], v7, v9
	v_mov_b32_e32 v9, v25
	s_nop 0
	v_cndmask_b32_e64 v7, 0, 1, s[42:43]
	v_cndmask_b32_e32 v7, v7, v8, vcc
	v_and_b32_e32 v7, 1, v7
	v_cmp_eq_u32_e64 s[42:43], 1, v7
	v_bitop3_b32 v7, v15, v16, 3 bitop3:0x36
	v_lshl_or_b32 v44, v7, 4, v17
	v_lshrrev_b32_e32 v7, 10, v76
	v_lshl_add_u32 v80, v7, 14, 0
	v_mul_u32_u24_e32 v46, 0xa00, v7
	v_lshrrev_b32_e32 v7, 10, v81
	v_lshl_add_u32 v82, v7, 14, 0
	v_mul_u32_u24_e32 v48, 0xa00, v7
	v_bitop3_b32 v7, v65, v12, 7 bitop3:0x6c
	v_lshlrev_b32_e32 v50, 4, v7
	v_lshrrev_b32_e32 v7, 8, v76
	v_lshlrev_b32_e32 v84, 12, v7
	v_bitop3_b32 v7, v7, v65, 7 bitop3:0x78
	v_lshlrev_b32_e32 v52, 4, v7
	v_or_b32_e32 v7, 4, v12
	v_lshlrev_b32_e32 v85, 12, v7
	v_bitop3_b32 v7, v12, v16, 4 bitop3:0x36
	v_lshl_add_u64 v[12:13], s[80:81], 0, v[24:25]
	s_ashr_i32 s80, s33, 2
	s_ashr_i32 s81, s80, 31
	s_lshl_b64 s[82:83], s[80:81], 18
	v_lshl_add_u64 v[12:13], v[12:13], 0, s[82:83]
	v_lshl_add_u64 v[12:13], v[12:13], 0, v[56:57]
	s_lshl_b64 s[80:81], s[80:81], 13
	v_add_co_u32_e32 v14, vcc, s65, v12
	s_add_u32 s44, s44, s80
	s_nop 0
	v_addc_co_u32_e32 v15, vcc, 0, v13, vcc
	s_movk_i32 s65, 0x2000
	s_addc_u32 s45, s45, s81
	v_add_co_u32_e32 v16, vcc, s65, v12
	v_lshlrev_b32_e32 v54, 4, v7
; #define LAS __attribute__((address_space(3)))
; #define PP_FETCH(task_) do { const int c_ = (task_) >> 2, h_ = (task_) & 3; const size_t t0_ = (size_t)c_ * 64; \
;         n_lr = *(const f32x4*)(LR + t0_ * 32 + tid * 4); \
;         _Pragma("unroll") for (int r_ = 0; r_ < 8; ++r_) { const bf16_t* rp_ = PG + (t0_ + rg * 8 + r_) * 2048 + h_ * 128 + c0; n_q[r_] = *(const unsigned*)rp_; n_k[r_] = *(const unsigned*)(rp_ + 512); } } while (0)
; DI void phase_gla_prep(const Params& P, int l, int bid, int nb, LAS unsigned char* lds) {
;     ...
;     if (bid < 2560) PP_FETCH(bid);
;     f32x2 bbs[2] = {{0.f, 0.f}, {0.f, 0.f}};
;     for (int task = bid; task < 2560; task += nb) {
;         const int c = task >> 2, h = task & 3;
;         __syncthreads();
;         if (h != hcur) { hcur = h;
;             for (int e = tid; e < 2 * 16 * 128; e += NTHR) { const int dir = e >> 11, k = (e >> 7) & 15, cc = e & 127;
;                 ((LAS float*)(lds + PP_W))[e] = (dir ? P.w_gk_b : P.w_gk_f)[(size_t)l * 16 * 512 + k * 512 + h * 128 + cc]; }
;             bbs[0] = *(const f32x2*)(P.b_gk_f + l * 512 + h * 128 + c0); bbs[1] = *(const f32x2*)(P.b_gk_b + l * 512 + h * 128 + c0); }
;         *(LAS f32x4*)(lds + PP_LR + tid * 16) = n_lr;
;         unsigned qw[8], kw[8];
; #pragma unroll
;         for (int r = 0; r < 8; ++r) { qw[r] = n_q[r]; kw[r] = n_k[r]; }
;         asm volatile("" : "+v"(qw[0]), "+v"(qw[1]), "+v"(qw[2]), "+v"(qw[3]), "+v"(qw[4]), "+v"(qw[5]), "+v"(qw[6]), "+v"(qw[7]), "+v"(kw[0]), "+v"(kw[1]), "+v"(kw[2]), "+v"(kw[3]), "+v"(kw[4]), "+v"(kw[5]), "+v"(kw[6]), "+v"(kw[7]) :: "memory");
;         __builtin_amdgcn_sched_barrier(0);
;         { const int wu = __builtin_amdgcn_readfirstlane(wid);
; #pragma unroll
;           for (int q = 0; q < 4; ++q) { const int row = wu * 8 + q * 2 + (lane >> 5);
;               __builtin_amdgcn_global_load_lds((const unsigned*)(PG + ((size_t)c * 64 + row) * 2048 + 1024 + h * 256 + (lane & 31) * 8), (LAS unsigned*)(lds + PP_V + (wu * 8 + q * 2) * 512), 16, 0, 0); } }
;         if (task + nb < 2560) PP_FETCH(task + nb);
	s_nop 0
	v_addc_co_u32_e32 v17, vcc, 0, v13, vcc
	global_load_dwordx4 v[18:21], v22, s[44:45]
	global_load_dword v177, v[16:17], off offset:-4096
	global_load_dword v179, v[16:17], off
	global_load_dword v180, v[16:17], off offset:1024
	s_movk_i32 s44, 0x3000
	v_add_co_u32_e32 v16, vcc, s44, v12
	s_movk_i32 s44, 0x4000
	s_nop 0
	v_addc_co_u32_e32 v17, vcc, 0, v13, vcc
	v_add_co_u32_e32 v58, vcc, s44, v12
	s_movk_i32 s44, 0x5000
	s_nop 0
	v_addc_co_u32_e32 v59, vcc, 0, v13, vcc
	v_add_co_u32_e32 v60, vcc, s44, v12
	s_movk_i32 s44, 0x6000
	s_nop 0
	v_addc_co_u32_e32 v61, vcc, 0, v13, vcc
	v_add_co_u32_e32 v62, vcc, s44, v12
	s_movk_i32 s44, 0x7000
	s_nop 0
	v_addc_co_u32_e32 v63, vcc, 0, v13, vcc
	global_load_dword v188, v[58:59], off offset:-4096
	global_load_dword v189, v[58:59], off
	global_load_dword v190, v[58:59], off offset:1024
	global_load_dword v196, v[62:63], off offset:-4096
	global_load_dword v204, v[62:63], off
	global_load_dword v205, v[62:63], off offset:1024
	v_add_co_u32_e32 v58, vcc, s44, v12
	v_lshrrev_b32_e32 v7, 8, v81
	s_nop 0
	v_addc_co_u32_e32 v59, vcc, 0, v13, vcc
	global_load_dword v181, v[12:13], off
	global_load_dword v182, v[12:13], off offset:1024
	global_load_dword v195, v[14:15], off offset:1024
	global_load_dword v199, v[16:17], off offset:1024
	global_load_dword v212, v[60:61], off offset:1024
	global_load_dword v216, v[58:59], off
	global_load_dword v217, v[58:59], off offset:1024
	v_lshlrev_b32_e32 v12, 12, v7
	v_bitop3_b32 v7, v7, v65, 7 bitop3:0x78
	v_lshlrev_b32_e32 v58, 4, v7
	v_mov_b32_e32 v7, v25
	v_lshl_add_u64 v[60:61], s[54:55], 0, v[6:7]
	v_lshl_add_u64 v[62:63], s[58:59], 0, v[6:7]
	v_lshl_add_u64 v[6:7], s[50:51], 0, v[6:7]
	s_mov_b64 s[44:45], 0x3b670000
	v_lshl_add_u64 v[64:65], v[6:7], 0, s[44:45]
	v_lshl_add_u64 v[6:7], s[50:51], 0, v[22:23]
	s_mov_b64 s[44:45], 0x30270000
	v_lshl_add_u64 v[70:71], v[6:7], 0, s[44:45]
	s_mov_b64 s[44:45], 0x36670000
	v_lshl_add_u64 v[74:75], v[4:5], 0, s[44:45]
	v_lshlrev_b32_e32 v4, 2, v76
	s_movk_i32 s54, 0x1e00
	v_and_or_b32 v184, v4, s54, v78
	v_add_u32_e32 v185, s70, v4
	v_or_b32_e32 v4, 0x1000, v3
	v_and_or_b32 v186, v4, s54, v78
	v_add_u32_e32 v187, s70, v4
	v_mov_b32_e32 v4, s57
	v_mov_b32_e32 v5, s53
	v_cmp_gt_u32_e32 vcc, s64, v136
	v_lshlrev_b32_e32 v8, 4, v76
	s_movk_i32 s44, 0xe00
	v_cndmask_b32_e32 v77, v4, v5, vcc
	v_mov_b32_e32 v4, s56
	v_mov_b32_e32 v5, s52
	v_cndmask_b32_e32 v76, v4, v5, vcc
	v_lshlrev_b32_e32 v4, 2, v81
	v_and_or_b32 v191, v4, s54, v78
	v_add_u32_e32 v192, s70, v4
	v_add_u32_e32 v4, 0x2800, v3
	v_and_or_b32 v193, v4, s54, v78
	v_add_u32_e32 v194, s70, v4
	v_or_b32_e32 v4, 0xc00, v136
	v_and_or_b32 v23, v3, s44, v78
	v_lshlrev_b32_e32 v5, 2, v4
	v_add_u32_e32 v3, 0x3800, v3
	v_and_or_b32 v197, v5, s54, v78
	v_and_or_b32 v201, v3, s54, v78
	v_lshlrev_b32_e32 v78, 1, v2
	v_mbcnt_lo_u32_b32 v2, -1, 0
	v_and_b32_e32 v8, 0x3ff0, v8
	v_mov_b32_e32 v24, v25
	v_mbcnt_hi_u32_b32 v213, -1, v2
	v_mov_b32_e32 v2, 0x80
	v_mov_b32_e32 v59, v25
	v_lshl_add_u64 v[68:69], s[78:79], 0, v[8:9]
	v_add_u32_e32 v198, s70, v5
	v_cmp_gt_u32_e64 s[44:45], s44, v4
	v_add_u32_e32 v203, s70, v3
	s_mov_b32 s70, -1
	s_mov_b64 s[54:55], 0x800
	s_mov_b64 s[58:59], 0x29e76000
	s_mov_b64 s[78:79], 0x29e74000
	v_add_u32_e32 v206, v80, v8
	v_add_u32_e32 v207, v82, v10
	v_add_u32_e32 v209, v79, v84
	v_add_u32_e32 v210, v79, v85
	v_add_u32_e32 v211, v79, v12
	v_lshl_or_b32 v214, v213, 2, v2
	v_mov_b64_e32 v[82:83], v[24:25]
	v_mov_b64_e32 v[80:81], v[24:25]
	s_mov_b32 s80, s33
	s_ashr_i32 s68, s80, 2
	s_ashr_i32 s69, s68, 31
	s_lshl_b64 s[68:69], s[68:69], 18
	s_add_u32 s68, s74, s68
	s_addc_u32 s69, s75, s69
	s_add_u32 s68, s68, s54
	s_addc_u32 s69, s69, s55
	s_and_b32 s32, s80, 3
	s_lshl_b32 s32, s32, 9
	s_add_u32 s68, s68, s32
	s_addc_u32 s69, s69, 0
	v_readfirstlane_b32 s95, v137
	s_lshl_b32 s32, s95, 12
	s_addk_i32 s32, 0x2000
	s_lshl_b32 s95, s95, 3
	v_or_b32_e32 v85, s95, v139
	v_lshl_add_u32 v85, v85, 12, v78
	s_mov_b32 m0, s32
	s_nop 0
	global_load_lds_dwordx4 v85, s[68:69]
	v_add_u32_e32 v84, 0x2000, v85
	s_add_i32 m0, s32, 0x400
	s_nop 0
	global_load_lds_dwordx4 v84, s[68:69]
	v_add_u32_e32 v84, 0x4000, v85
	s_add_i32 m0, s32, 0x800
	s_nop 0
	global_load_lds_dwordx4 v84, s[68:69]
	v_add_u32_e32 v84, 0x6000, v85
	s_add_i32 m0, s32, 0xc00
	s_nop 0
	global_load_lds_dwordx4 v84, s[68:69]
	s_mov_b32 s66, 0x1c000
	s_mov_b32 s67, 0x1c000
	s_waitcnt vmcnt(0)
	s_branch .LBB0_898
; #define LAS __attribute__((address_space(3)))
; DI unsigned pkbf(float a, float b) { f32x2 v = {a, b}; bfx2 r = __builtin_convertvector(v, bfx2); return __builtin_bit_cast(unsigned, r); }
; DI void phase_gla_prep(const Params& P, int l, int bid, int nb, LAS unsigned char* lds) {
;     ...
;         { const int dir = wid >> 2, ti = (wid >> 1) & 1, tj = wid & 1; const int i = ti * 32 + r32, jr = tj * 32 + r32;
;           f32x16 acc; for (int x = 0; x < 16; ++x) acc[x] = 0.f;
; #pragma unroll
;           for (int s = 0; s < 8; ++s) { const int ch = 2 * s + hi;
;               const bf16x8 a = *(const LAS bf16x8*)(lds + PP_KD + dir * 16384 + jr * 256 + ((ch ^ (jr & 15)) << 4));
;               const bf16x8 b = *(const LAS bf16x8*)(lds + PP_QD + dir * 16384 + i * 256 + ((ch ^ (i & 15)) << 4));
;               acc = __builtin_amdgcn_mfma_f32_32x32x16_bf16(a, b, acc, 0, 0, 0); }
;           unsigned char* am = P.ws + GL_PD + ((size_t)dir * 2560 + task) * GL_PD_BYTES + 16384;
; #pragma unroll
;           for (int a4 = 0; a4 < 4; ++a4) { float v[4];
; #pragma unroll
;               for (int b4 = 0; b4 < 4; ++b4) { const int j = tj * 32 + 8 * a4 + 4 * hi + b4; const bool keep = dir ? (j >= i) : (j <= i); v[b4] = keep ? acc[a4 * 4 + b4] : 0.f; }
;               u32x2 w; w.x = pkbf(v[0], v[1]); w.y = pkbf(v[2], v[3]);
;               *(u32x2*)(am + i * 128 + ((((4 * tj + a4) ^ ((i >> 1) & 7)) << 4) | (hi << 3))) = w; } }
; #pragma unroll
;         for (int q = 0; q < 4; ++q) { const int e = q * 512 + tid, dir = e >> 10, o = (e & 1023) * 16;
;             *(u32x4*)(P.ws + GL_PD + ((size_t)dir * 2560 + task) * GL_PD_BYTES + o) = *(const LAS u32x4*)(lds + PP_QD + dir * 16384 + o); }
; #pragma unroll
;         for (int q = 0; q < 4; ++q) { const int e = q * 512 + tid, v = e & 255, jo = e >> 8; unsigned short t[8];
; #pragma unroll
;             for (int x = 0; x < 8; ++x) t[x] = *(const LAS unsigned short*)(lds + PP_V + (jo * 8 + x) * 512 + v * 2);
;             u32x4 w; w.x = t[0] | ((unsigned)t[1] << 16); w.y = t[2] | ((unsigned)t[3] << 16); w.z = t[4] | ((unsigned)t[5] << 16); w.w = t[6] | ((unsigned)t[7] << 16);
;             *(u32x4*)(P.ws + GL_VT + (size_t)task * 32768 + v * 128 + ((jo ^ ((v >> 1) & 7)) << 4)) = w; }
.LBB0_897:
	v_add_u32_e32 v2, v140, v169
	s_waitcnt lgkmcnt(0)
	s_barrier
	ds_read_b128 v[2:5], v2
	v_add_u32_e32 v6, v141, v169
	ds_read_b128 v[6:9], v6 offset:40960
	v_add_u32_e32 v79, v140, v170
	ds_read_b128 v[84:87], v79
	v_add_u32_e32 v79, v141, v170
	s_waitcnt lgkmcnt(1)
	v_mfma_f32_32x32x16_bf16 v[2:17], v[2:5], v[6:9], 0
	ds_read_b128 v[88:91], v79 offset:40960
	v_add_u32_e32 v79, v140, v171
	v_add_u32_e32 v96, v141, v175
	v_add_u32_e32 v97, v141, v176
	v_lshl_add_u64 v[100:101], s[80:81], 0, v[34:35]
	v_mov_b64_e32 v[102:103], s[50:51]
	s_and_b64 vcc, exec, s[82:83]
	s_waitcnt lgkmcnt(0)
	v_mfma_f32_32x32x16_bf16 v[2:17], v[84:87], v[88:91], v[2:17]
	ds_read_b128 v[84:87], v79
	v_add_u32_e32 v79, v141, v171
	ds_read_b128 v[88:91], v79 offset:40960
	v_add_u32_e32 v79, v140, v172
	s_waitcnt lgkmcnt(0)
	v_mfma_f32_32x32x16_bf16 v[2:17], v[84:87], v[88:91], v[2:17]
	ds_read_b128 v[84:87], v79
	v_add_u32_e32 v79, v141, v172
	ds_read_b128 v[88:91], v79 offset:40960
	v_add_u32_e32 v79, v140, v173
	s_waitcnt lgkmcnt(0)
	v_mfma_f32_32x32x16_bf16 v[2:17], v[84:87], v[88:91], v[2:17]
	ds_read_b128 v[84:87], v79
	v_add_u32_e32 v79, v141, v173
	ds_read_b128 v[88:91], v79 offset:40960
	v_add_u32_e32 v79, v140, v174
	s_waitcnt lgkmcnt(0)
	v_mfma_f32_32x32x16_bf16 v[2:17], v[84:87], v[88:91], v[2:17]
	ds_read_b128 v[84:87], v79
	v_add_u32_e32 v79, v141, v174
	ds_read_b128 v[88:91], v79 offset:40960
	v_add_u32_e32 v79, v140, v175
	ds_read_b128 v[92:95], v79
	s_waitcnt lgkmcnt(1)
	v_mfma_f32_32x32x16_bf16 v[2:17], v[84:87], v[88:91], v[2:17]
	ds_read_b128 v[84:87], v96 offset:40960
	v_add_u32_e32 v79, v140, v176
	ds_read_b128 v[88:91], v79
	ds_read_b128 v[96:99], v97 offset:40960
	s_waitcnt lgkmcnt(2)
	v_mfma_f32_32x32x16_bf16 v[2:17], v[92:95], v[84:87], v[2:17]
	v_mad_u64_u32 v[84:85], s[84:85], v100, s91, v[102:103]
	v_mad_i32_i24 v85, v101, s91, v85
	v_lshl_add_u64 v[84:85], v[84:85], 0, v[36:37]
	v_lshl_add_u64 v[84:85], v[84:85], 0, s[78:79]
	v_lshl_add_u64 v[86:87], v[84:85], 0, v[38:39]
	v_lshl_add_u64 v[92:93], v[84:85], 0, v[40:41]
	s_waitcnt lgkmcnt(0)
	v_mfma_f32_32x32x16_bf16 v[2:17], v[88:91], v[96:99], v[2:17]
	v_lshl_add_u64 v[94:95], v[84:85], 0, v[42:43]
	s_nop 10
	v_cndmask_b32_e64 v2, 0, v2, s[10:11]
	v_cndmask_b32_e64 v3, 0, v3, s[12:13]
	v_cndmask_b32_e64 v4, 0, v4, s[14:15]
	v_cndmask_b32_e64 v5, 0, v5, s[16:17]
	v_cndmask_b32_e64 v6, 0, v6, s[18:19]
	v_cndmask_b32_e64 v7, 0, v7, s[20:21]
	v_cndmask_b32_e64 v8, 0, v8, s[22:23]
	v_cndmask_b32_e64 v9, 0, v9, s[24:25]
	v_cndmask_b32_e64 v10, 0, v10, s[26:27]
	v_cndmask_b32_e64 v11, 0, v11, s[28:29]
	v_cndmask_b32_e64 v12, 0, v12, s[30:31]
	v_cndmask_b32_e64 v13, 0, v13, s[34:35]
	v_cvt_pk_bf16_f32 v2, v2, v3
	v_cvt_pk_bf16_f32 v3, v4, v5
	v_cndmask_b32_e64 v16, 0, v16, s[40:41]
	v_cvt_pk_bf16_f32 v4, v6, v7
	v_cvt_pk_bf16_f32 v5, v8, v9
	v_cvt_pk_bf16_f32 v6, v10, v11
	v_cvt_pk_bf16_f32 v7, v12, v13
	global_store_dwordx2 v[86:87], v[2:3], off
	global_store_dwordx2 v[92:93], v[4:5], off
	global_store_dwordx2 v[94:95], v[6:7], off
	v_cndmask_b32_e64 v2, 0, v17, s[42:43]
	v_cvt_pk_bf16_f32 v7, v16, v2
	ds_read_b128 v[2:5], v24 offset:40960
	v_cndmask_b32_e64 v14, 0, v14, s[36:37]
	v_cndmask_b32_e64 v15, 0, v15, s[38:39]
	v_cvt_pk_bf16_f32 v6, v14, v15
	v_lshl_add_u64 v[8:9], v[84:85], 0, v[44:45]
	v_mad_i64_i32 v[10:11], s[84:85], s80, v215, v[66:67]
	global_store_dwordx2 v[8:9], v[6:7], off
	ds_read_b128 v[6:9], v24 offset:57344
	s_waitcnt lgkmcnt(1)
	global_store_dwordx4 v[10:11], v[2:5], off
	ds_read_b128 v[2:5], v206 offset:40960
	v_lshl_add_u64 v[10:11], s[80:81], 0, v[46:47]
	v_mad_u64_u32 v[14:15], s[84:85], v10, s91, v[68:69]
	v_mad_i32_i24 v15, v11, s91, v15
	ds_read_b128 v[10:13], v207 offset:40960
	s_waitcnt lgkmcnt(1)
	global_store_dwordx4 v[14:15], v[2:5], off
	s_nop 1
	v_mad_i64_i32 v[2:3], s[84:85], s80, v215, v[70:71]
	global_store_dwordx4 v[2:3], v[6:9], off
	v_lshl_add_u64 v[2:3], s[80:81], 0, v[48:49]
	v_mad_u64_u32 v[4:5], s[84:85], v2, s91, v[72:73]
	v_mad_i32_i24 v5, v3, s91, v5
	s_waitcnt lgkmcnt(0)
	global_store_dwordx4 v[4:5], v[10:13], off
	ds_read_u16 v2, v208 offset:8192
	ds_read_u16 v3, v208 offset:8704
	ds_read_u16 v4, v208 offset:9216
	ds_read_u16 v5, v208 offset:9728
	ds_read_u16 v6, v208 offset:10240
	ds_read_u16 v7, v208 offset:10752
	ds_read_u16 v8, v208 offset:11264
	ds_read_u16 v9, v208 offset:11776
	ds_read_u16 v10, v209 offset:8192
	ds_read_u16 v11, v209 offset:8704
	ds_read_u16 v12, v209 offset:9216
	ds_read_u16 v13, v209 offset:9728
	ds_read_u16 v14, v209 offset:10240
	ds_read_u16 v15, v209 offset:10752
	ds_read_u16 v16, v209 offset:11264
	ds_read_u16 v17, v209 offset:11776
	s_lshl_b64 s[80:81], s[80:81], 15
	s_waitcnt lgkmcnt(14)
	v_lshl_or_b32 v2, v3, 16, v2
	s_waitcnt lgkmcnt(12)
	v_lshl_or_b32 v3, v5, 16, v4
	s_waitcnt lgkmcnt(10)
	v_lshl_or_b32 v4, v7, 16, v6
	v_lshl_add_u64 v[6:7], v[74:75], 0, s[80:81]
	s_waitcnt lgkmcnt(8)
	v_lshl_or_b32 v5, v9, 16, v8
	v_lshl_add_u64 v[8:9], v[6:7], 0, v[50:51]
	global_store_dwordx4 v[8:9], v[2:5], off
	v_lshl_add_u64 v[8:9], v[6:7], 0, v[52:53]
	s_mov_b32 s80, s71
	s_waitcnt lgkmcnt(6)
	v_lshl_or_b32 v2, v11, 16, v10
	s_waitcnt lgkmcnt(4)
	v_lshl_or_b32 v3, v13, 16, v12
	s_waitcnt lgkmcnt(2)
	v_lshl_or_b32 v4, v15, 16, v14
	s_waitcnt lgkmcnt(0)
	v_lshl_or_b32 v5, v17, 16, v16
	ds_read_u16 v10, v210 offset:8192
	ds_read_u16 v11, v210 offset:8704
	ds_read_u16 v12, v210 offset:9216
	ds_read_u16 v13, v210 offset:9728
	ds_read_u16 v14, v210 offset:10240
	ds_read_u16 v15, v210 offset:10752
	ds_read_u16 v16, v210 offset:11264
	ds_read_u16 v17, v210 offset:11776
	global_store_dwordx4 v[8:9], v[2:5], off
	v_lshl_add_u64 v[8:9], v[6:7], 0, v[54:55]
	v_lshl_add_u64 v[6:7], v[6:7], 0, v[58:59]
	s_waitcnt lgkmcnt(6)
	v_lshl_or_b32 v2, v11, 16, v10
	s_waitcnt lgkmcnt(4)
	v_lshl_or_b32 v3, v13, 16, v12
	s_waitcnt lgkmcnt(2)
	v_lshl_or_b32 v4, v15, 16, v14
	s_waitcnt lgkmcnt(0)
	v_lshl_or_b32 v5, v17, 16, v16
	ds_read_u16 v10, v211 offset:8192
	ds_read_u16 v11, v211 offset:8704
	ds_read_u16 v12, v211 offset:9216
	ds_read_u16 v13, v211 offset:9728
	ds_read_u16 v14, v211 offset:10240
	ds_read_u16 v15, v211 offset:10752
	ds_read_u16 v16, v211 offset:11264
	ds_read_u16 v17, v211 offset:11776
	global_store_dwordx4 v[8:9], v[2:5], off
	s_waitcnt lgkmcnt(6)
	s_nop 0
	v_lshl_or_b32 v2, v11, 16, v10
	s_waitcnt lgkmcnt(4)
	v_lshl_or_b32 v3, v13, 16, v12
	s_waitcnt lgkmcnt(2)
	v_lshl_or_b32 v4, v15, 16, v14
	s_waitcnt lgkmcnt(0)
	v_lshl_or_b32 v5, v17, 16, v16
	global_store_dwordx4 v[6:7], v[2:5], off
	v_add_u32_e32 v208, s67, v208
	v_add_u32_e32 v209, s67, v209
	v_add_u32_e32 v210, s67, v210
	v_add_u32_e32 v211, s67, v211
	s_sub_i32 s67, 0, s67
	s_xor_b32 s66, s66, 0x1c000
	s_cbranch_vccnz .LBB0_912

; #define LAS __attribute__((address_space(3)))
; #define PP_FETCH(task_) do { const int c_ = (task_) >> 2, h_ = (task_) & 3; const size_t t0_ = (size_t)c_ * 64; \
;         n_lr = *(const f32x4*)(LR + t0_ * 32 + tid * 4); \
;         _Pragma("unroll") for (int r_ = 0; r_ < 8; ++r_) { const bf16_t* rp_ = PG + (t0_ + rg * 8 + r_) * 2048 + h_ * 128 + c0; n_q[r_] = *(const unsigned*)rp_; n_k[r_] = *(const unsigned*)(rp_ + 512); } } while (0)
; DI void phase_gla_prep(const Params& P, int l, int bid, int nb, LAS unsigned char* lds) {
;     ...
;         __syncthreads();
;         if (h != hcur) { hcur = h;
;             for (int e = tid; e < 2 * 16 * 128; e += NTHR) { const int dir = e >> 11, k = (e >> 7) & 15, cc = e & 127;
;                 ((LAS float*)(lds + PP_W))[e] = (dir ? P.w_gk_b : P.w_gk_f)[(size_t)l * 16 * 512 + k * 512 + h * 128 + cc]; }
;             bbs[0] = *(const f32x2*)(P.b_gk_f + l * 512 + h * 128 + c0); bbs[1] = *(const f32x2*)(P.b_gk_b + l * 512 + h * 128 + c0); }
;         *(LAS f32x4*)(lds + PP_LR + tid * 16) = n_lr;
;         unsigned qw[8], kw[8];
; #pragma unroll
;         for (int r = 0; r < 8; ++r) { qw[r] = n_q[r]; kw[r] = n_k[r]; }
;         asm volatile("" : "+v"(qw[0]), "+v"(qw[1]), "+v"(qw[2]), "+v"(qw[3]), "+v"(qw[4]), "+v"(qw[5]), "+v"(qw[6]), "+v"(qw[7]), "+v"(kw[0]), "+v"(kw[1]), "+v"(kw[2]), "+v"(kw[3]), "+v"(kw[4]), "+v"(kw[5]), "+v"(kw[6]), "+v"(kw[7]) :: "memory");
;         __builtin_amdgcn_sched_barrier(0);
;         { const int wu = __builtin_amdgcn_readfirstlane(wid);
; #pragma unroll
;           for (int q = 0; q < 4; ++q) { const int row = wu * 8 + q * 2 + (lane >> 5);
;               __builtin_amdgcn_global_load_lds((const unsigned*)(PG + ((size_t)c * 64 + row) * 2048 + 1024 + h * 256 + (lane & 31) * 8), (LAS unsigned*)(lds + PP_V + (wu * 8 + q * 2) * 512), 16, 0, 0); } }
;         if (task + nb < 2560) PP_FETCH(task + nb);
;         asm volatile("s_waitcnt lgkmcnt(0)" ::: "memory"); __builtin_amdgcn_s_barrier(); asm volatile("" ::: "memory");
.LBB0_901:
	s_or_b64 exec, exec, s[82:83]
	s_lshl_b32 s76, s70, 2
	v_lshl_add_u64 v[2:3], v[60:61], 0, s[76:77]
	global_load_dwordx2 v[80:81], v[2:3], off offset:2048
	v_lshl_add_u64 v[2:3], v[62:63], 0, s[76:77]
	global_load_dwordx2 v[82:83], v[2:3], off offset:2048
	s_waitcnt vmcnt(0)
	s_mov_b32 s70, s71
.LBB0_902:
	v_add_u32_e32 v24, 0, v22
	ds_write_b128 v24, v[18:21]
	v_mov_b32_e32 v7, v189
	v_mov_b32_e32 v9, v199
	v_mov_b32_e32 v3, v204
	v_mov_b32_e32 v5, v212
	v_mov_b32_e32 v13, v177
	v_mov_b32_e32 v15, v182
	v_mov_b32_e32 v2, v217
	v_mov_b32_e32 v11, v188
	v_mov_b32_e32 v12, v180
	v_mov_b32_e32 v8, v196
	v_mov_b32_e32 v10, v190
	v_mov_b32_e32 v17, v181
	v_mov_b32_e32 v4, v216
	v_mov_b32_e32 v6, v205
	v_mov_b32_e32 v14, v179
	v_mov_b32_e32 v16, v195
	s_add_i32 s71, s80, s94
	s_cmpk_gt_i32 s71, 0x9ff
	s_cselect_b64 s[82:83], -1, 0
	s_and_b64 vcc, exec, s[82:83]
	s_cbranch_vccnz .LBB0_904
	s_ashr_i32 s84, s71, 2
	s_lshl_b32 s64, s71, 8
	s_ashr_i32 s85, s84, 31
	s_and_b32 s76, s64, 0x300
	s_lshl_b64 s[86:87], s[84:85], 13
	v_lshl_add_u64 v[20:21], v[28:29], 0, s[76:77]
	s_lshl_b64 s[84:85], s[84:85], 18
	v_lshl_add_u64 v[20:21], v[20:21], 0, s[84:85]
	v_lshl_add_u64 v[84:85], v[20:21], 0, v[56:57]
	v_add_co_u32_e32 v86, vcc, 0x1000, v84
	v_lshl_add_u64 v[18:19], v[26:27], 0, s[86:87]
	s_nop 0
	v_addc_co_u32_e32 v87, vcc, 0, v85, vcc
	v_add_co_u32_e32 v88, vcc, 0x2000, v84
	global_load_dwordx4 v[18:21], v[18:19], off
	s_nop 0
	global_load_dword v181, v[84:85], off
	global_load_dword v182, v[84:85], off offset:1024
	global_load_dword v177, v[86:87], off
	v_addc_co_u32_e32 v89, vcc, 0, v85, vcc
	v_add_co_u32_e32 v90, vcc, 0x3000, v84
	s_nop 1
	v_addc_co_u32_e32 v91, vcc, 0, v85, vcc
	v_add_co_u32_e32 v92, vcc, 0x4000, v84
	s_nop 1
	v_addc_co_u32_e32 v93, vcc, 0, v85, vcc
	v_add_co_u32_e32 v94, vcc, 0x5000, v84
	s_nop 1
	v_addc_co_u32_e32 v95, vcc, 0, v85, vcc
	global_load_dword v195, v[86:87], off offset:1024
	global_load_dword v179, v[88:89], off
	global_load_dword v180, v[88:89], off offset:1024
	global_load_dword v188, v[90:91], off
	global_load_dword v199, v[90:91], off offset:1024
	global_load_dword v189, v[92:93], off
	global_load_dword v190, v[92:93], off offset:1024
	global_load_dword v196, v[94:95], off
	v_add_co_u32_e32 v86, vcc, 0x6000, v84
	s_nop 1
	v_addc_co_u32_e32 v87, vcc, 0, v85, vcc
	v_add_co_u32_e32 v84, vcc, 0x7000, v84
	s_nop 1
	v_addc_co_u32_e32 v85, vcc, 0, v85, vcc
	global_load_dword v212, v[94:95], off offset:1024
	global_load_dword v204, v[86:87], off
	global_load_dword v205, v[86:87], off offset:1024
	global_load_dword v216, v[84:85], off
	global_load_dword v217, v[84:85], off offset:1024
	s_ashr_i32 s68, s71, 2
	s_ashr_i32 s69, s68, 31
	s_lshl_b64 s[68:69], s[68:69], 18
	s_add_u32 s68, s74, s68
	s_addc_u32 s69, s75, s69
	s_add_u32 s68, s68, s54
	s_addc_u32 s69, s69, s55
	s_and_b32 s32, s71, 3
	s_lshl_b32 s32, s32, 9
	s_add_u32 s68, s68, s32
	s_addc_u32 s69, s69, 0
	v_readfirstlane_b32 s95, v137
	s_lshl_b32 s32, s95, 12
	s_add_i32 s32, s32, s66
	s_addk_i32 s32, 0x2000
	s_lshl_b32 s95, s95, 3
	v_or_b32_e32 v85, s95, v139
	v_lshl_add_u32 v85, v85, 12, v78
	s_mov_b32 m0, s32
	s_nop 0
	global_load_lds_dwordx4 v85, s[68:69]
	v_add_u32_e32 v84, 0x2000, v85
	s_add_i32 m0, s32, 0x400
	s_nop 0
	global_load_lds_dwordx4 v84, s[68:69]
	v_add_u32_e32 v84, 0x4000, v85
	s_add_i32 m0, s32, 0x800
	s_nop 0
	global_load_lds_dwordx4 v84, s[68:69]
	v_add_u32_e32 v84, 0x6000, v85
	s_add_i32 m0, s32, 0xc00
	s_nop 0
	global_load_lds_dwordx4 v84, s[68:69]
.LBB0_904:
	v_lshlrev_b32_e32 v114, 16, v2
	v_and_b32_e32 v115, 0xffff0000, v2
	v_and_b32_e32 v2, 63, v213
	v_cmp_gt_u32_e32 vcc, 56, v2
	v_lshlrev_b32_e32 v108, 16, v3
	v_and_b32_e32 v109, 0xffff0000, v3
	v_cndmask_b32_e64 v3, 0, 8, vcc
	v_cmp_gt_u32_e32 vcc, 48, v2
	v_add_lshl_u32 v79, v3, v213, 2
	s_waitcnt lgkmcnt(0)
	s_barrier
	v_cndmask_b32_e64 v2, 0, 16, vcc
	v_add_lshl_u32 v218, v2, v213, 2
	v_and_b32_e32 v2, 64, v213
	v_or_b32_e32 v3, v2, v138
	v_lshlrev_b32_e32 v219, 2, v3
	v_add_u32_e32 v3, -8, v213
	v_cmp_lt_i32_e32 vcc, v3, v2
	s_ashr_i32 s81, s80, 31
	v_lshlrev_b32_e32 v84, 16, v17
	v_cndmask_b32_e32 v3, v3, v213, vcc
	v_lshlrev_b32_e32 v220, 2, v3
	v_add_u32_e32 v3, -16, v213
	v_cmp_lt_i32_e32 vcc, v3, v2
	v_and_b32_e32 v85, 0xffff0000, v17
	v_lshlrev_b32_e32 v86, 16, v15
	v_cndmask_b32_e32 v3, v3, v213, vcc
	v_lshlrev_b32_e32 v221, 2, v3
	v_subrev_u32_e32 v3, 32, v213
	v_cmp_lt_i32_e32 vcc, v3, v2
	v_and_b32_e32 v87, 0xffff0000, v15
	v_lshlrev_b32_e32 v88, 16, v13
	v_cndmask_b32_e32 v2, v3, v213, vcc
	v_and_b32_e32 v89, 0xffff0000, v13
	v_lshlrev_b32_e32 v90, 16, v16
	v_and_b32_e32 v91, 0xffff0000, v16
	v_lshlrev_b32_e32 v92, 16, v14
	v_and_b32_e32 v93, 0xffff0000, v14
	v_lshlrev_b32_e32 v94, 16, v12
	v_and_b32_e32 v95, 0xffff0000, v12
	v_lshlrev_b32_e32 v96, 16, v11
	v_and_b32_e32 v97, 0xffff0000, v11
	v_lshlrev_b32_e32 v98, 16, v9
	v_and_b32_e32 v99, 0xffff0000, v9
	v_lshlrev_b32_e32 v100, 16, v7
	v_and_b32_e32 v101, 0xffff0000, v7
	v_lshlrev_b32_e32 v102, 16, v10
	v_and_b32_e32 v103, 0xffff0000, v10
	v_lshlrev_b32_e32 v104, 16, v8
	v_and_b32_e32 v105, 0xffff0000, v8
	v_lshlrev_b32_e32 v106, 16, v5
	v_and_b32_e32 v107, 0xffff0000, v5
	v_lshlrev_b32_e32 v110, 16, v6
	v_and_b32_e32 v111, 0xffff0000, v6
	v_lshlrev_b32_e32 v112, 16, v4
	v_and_b32_e32 v113, 0xffff0000, v4
	s_mov_b32 s76, 0
	v_lshlrev_b32_e32 v222, 2, v2
	v_or_b32_e32 v223, 0xe0, v219
	s_mov_b64 s[84:85], -1
	s_branch .LBB0_906
